# attention: skip per-unit bias-table rebuild when head unchanged; drop redundant self-max after row-max permlane swap
# baseline (speedup 1.0000x reference)
; #define KP_ ([]() { unsigned long long q_ = (unsigned long long)__builtin_amdgcn_kernarg_segment_ptr(); asm volatile("" : "+s"(q_)); return (const __attribute__((address_space(4))) Params*)q_; }())
; __device__ __forceinline__ void attn_unit(LAS unsigned char* lds, bf16_t* Zg, const unsigned char* KVg, int S, int b, int h, int qb, const float* lq1, const float* lk1, const float* lq2, const float* lk2, const float* subln_g, const float* rel_bias, bool dostore = true) {
;     ...
;     const float lam = __builtin_amdgcn_exp2f(LOG2E * wave_sum(lq1[lane] * lk1[lane], lane)) - __builtin_amdgcn_exp2f(LOG2E * wave_sum(lq2[lane] * lk2[lane], lane)) + LAMBDA_INIT;
; __global__ void __launch_bounds__(NTHREADS, 2) fwd_megakernel(Params P, int ph_lo, int ph_hi, int use_sync) {
;     ...
;             const int nqb = S / 128, nunits = NB * 8 * nqb;
;             for (int u = vcu; u < nunits; u += G) { const int bh = u / nqb, qb = u % nqb; attn_unit(lds, Z, ws + WS_KV, S, bh >> 3, bh & 7, qb, KP_->lq1, KP_->lk1, KP_->lq2, KP_->lk2, KP_->subln_g, KP_->rel_bias); }
.LBB0_185:
	s_ff1_i32_b32 s4, s11
	s_lshr_b32 s4, 0x8000, s4
	s_lshr_b32 s43, s11, 4
	s_mul_i32 s43, s43, s4
	s_cmp_ge_i32 s82, s43
	v_readlane_b32 s72, v229, 15
	s_cbranch_scc1 .LBB0_291
	s_mov_b32 s100, -1
	s_load_dwordx2 s[4:5], s[0:1], 0x20
	s_load_dwordx2 s[6:7], s[0:1], 0x28
	s_load_dwordx2 s[8:9], s[0:1], 0x30
	s_load_dwordx2 s[12:13], s[0:1], 0x38
	v_and_b32_e32 v66, 63, v204
	v_lshlrev_b32_e32 v66, 2, v66
	s_waitcnt lgkmcnt(0)
	global_load_dword v67, v66, s[4:5]
	global_load_dword v68, v66, s[6:7]
	global_load_dword v69, v66, s[8:9]
	global_load_dword v70, v66, s[12:13]
	v_xor_b32_e32 v84, 4, v66
	v_xor_b32_e32 v85, 8, v66
	v_xor_b32_e32 v86, 16, v66
	v_xor_b32_e32 v87, 32, v66
	v_xor_b32_e32 v88, 64, v66
	v_xor_b32_e32 v66, 0x80, v66
	s_waitcnt vmcnt(2)
	v_mul_f32_e32 v71, v67, v68
	ds_bpermute_b32 v71, v84, v71
	s_waitcnt vmcnt(0)
	v_mul_f32_e32 v72, v69, v70
	ds_bpermute_b32 v72, v84, v72
	s_waitcnt lgkmcnt(1)
	v_fmac_f32_e32 v71, v67, v68
	ds_bpermute_b32 v67, v85, v71
	s_waitcnt lgkmcnt(1)
	v_fmac_f32_e32 v72, v69, v70
	ds_bpermute_b32 v68, v85, v72
	s_waitcnt lgkmcnt(1)
	v_add_f32_e32 v67, v71, v67
	ds_bpermute_b32 v69, v86, v67
	s_waitcnt lgkmcnt(1)
	v_add_f32_e32 v68, v72, v68
	ds_bpermute_b32 v70, v86, v68
	s_waitcnt lgkmcnt(1)
	v_add_f32_e32 v67, v67, v69
	ds_bpermute_b32 v69, v87, v67
	s_waitcnt lgkmcnt(1)
	v_add_f32_e32 v68, v68, v70
	ds_bpermute_b32 v70, v87, v68
	s_waitcnt lgkmcnt(1)
	v_add_f32_e32 v67, v67, v69
	ds_bpermute_b32 v69, v88, v67
	s_waitcnt lgkmcnt(1)
	v_add_f32_e32 v68, v68, v70
	ds_bpermute_b32 v70, v88, v68
	s_waitcnt lgkmcnt(1)
	v_add_f32_e32 v67, v67, v69
	s_waitcnt lgkmcnt(0)
	v_add_f32_e32 v69, v68, v70
	ds_bpermute_b32 v68, v66, v67
	ds_bpermute_b32 v70, v66, v69
	s_waitcnt lgkmcnt(0)
	v_add_f32_e32 v69, v69, v70
	v_add_f32_e32 v67, v67, v68
	v_mul_f32_e32 v67, 0x3fb8aa3b, v67
	v_mul_f32_e32 v68, 0x3fb8aa3b, v69
	v_exp_f32_e32 v67, v67
	v_exp_f32_e32 v68, v68
	s_nop 0
	v_sub_f32_e32 v67, v67, v68
	v_add_f32_e32 v247, 0x3e4ccccd, v67
	s_lshr_b32 s66, s11, 7
	v_cvt_f32_ubyte0_e32 v0, s66
	v_writelane_b32 v229, s30, 19
	s_lshl_b32 s22, s11, 9
	s_add_i32 s4, s11, 0xffffff40
	v_rcp_iflag_f32_e32 v0, v0
	v_writelane_b32 v229, s4, 20
	s_add_i32 s5, s22, 0xffff0000
	v_writelane_b32 v229, s5, 21
	s_add_i32 s5, s11, 0xffffff7f
	v_writelane_b32 v229, s5, 22
	s_add_i32 s5, s11, 0xfffffee6
	v_writelane_b32 v229, s5, 23
	s_add_i32 s5, s22, 0xffff0400
	v_mul_f32_e32 v0, 0x4f7ffffe, v0
	v_writelane_b32 v229, s5, 24
	s_add_i32 s5, s22, 0xffffa000
	v_cvt_u32_f32_e32 v0, v0
	s_lshr_b32 s67, s11, 6
	v_writelane_b32 v229, s5, 25
	s_add_i32 s5, s11, 0xffffffbf
	s_add_i32 s4, s67, -1
	v_writelane_b32 v229, s5, 26
	s_add_i32 s5, s22, 0xffff8400
	s_lshl_b32 s46, s4, 15
	v_writelane_b32 v229, s5, 27
	s_lshl_b32 s4, s4, 6
	s_or_b32 s45, s4, 63
	v_writelane_b32 v229, s4, 28
	s_add_i32 s44, s4, 0xffffffa6
	s_sub_i32 s4, 0, s66
	v_readfirstlane_b32 s5, v0
	s_mul_i32 s4, s4, s5
	s_mul_hi_u32 s4, s5, s4
	s_add_i32 s24, s67, 0x1ffff
	s_add_i32 s58, s22, 0xffff8000
	s_add_i32 s41, s11, 0xffffff80
	s_or_b32 s48, s46, 0x2000
	s_sub_i32 s49, s11, 64
	s_add_i32 s34, s5, s4
	s_and_b32 s98, s11, 0x7f80
	s_mov_b32 s94, s82
	s_branch .LBB0_188

; #define LAS __attribute__((address_space(3)))
; #define ISSUE_K(tile, slot) do { const int s_ = (tile) << 15; DMAB(kvo, s_, 0, (slot) * 16384 + kdma); DMAB(kvo, s_ + 8192, 0, (slot) * 16384 + 8192 + kdma); } while (0)
; #define ISSUE_V(tile, slot) do { const int s_ = (tile) << 15; DMAB(vvo, s_, 0, (slot) * 16384 + vdma); DMAB(vvo, s_ + 1024, 0, (slot) * 16384 + vdma + 1024); } while (0)
; __device__ __forceinline__ void attn_unit(LAS unsigned char* lds, bf16_t* Zg, const unsigned char* KVg, int S, int b, int h, int qb, const float* lq1, const float* lk1, const float* lq2, const float* lk2, const float* subln_g, const float* rel_bias, bool dostore = true) {
;     ...
;     const size_t rowbase = (size_t)b * S; const int q0 = qb * 128, qw0 = q0 + 32 * qsub;
;     LAS float* tab = (LAS float*)(lds + 131072);
;     LAS float* wsf = (LAS float*)(lds + 131072 + 2304) + wid * 32;
;     const int NT = S / 64; const size_t tstep = (size_t)64 * ZLD;
;     const unsigned char* kvb = KVg + ((size_t)((b * 8 + h) * NT) << 15);
;     const __amdgpu_buffer_rsrc_t kvr = __builtin_amdgcn_make_buffer_rsrc((void*)kvb, (short)0, NT << 15, 0x00020000);
;     const unsigned kvo = wid * 1024 + lane * 16;
;     const unsigned vvo = 16384 + (wid >> 1) * 4096 + (wid & 1) * 2048 + lane * 16;
;     const unsigned kdma = wid * 1024, vdma = 65536 + (wid >> 1) * 4096 + (wid & 1) * 2048;
;     ...
;     ISSUE_K(0, 0); ISSUE_V(0, 0); ISSUE_K(1, 1); ISSUE_K(2, 2); ISSUE_V(1, 1);
;     for (int ti = tid; ti < 513; ti += 512) { const int rel = ti - 256, n = rel < 0 ? -rel : rel;
;         int bk = n < 8 ? n : n < 12 ? 8 : n < 16 ? 9 : n < 23 ? 10 : n < 32 ? 11 : n < 46 ? 12 : n < 64 ? 13 : n < 91 ? 14 : 15; if (rel > 0) bk += 16;
;         tab[ti] = rel_bias[bk * 8 + h] * LOG2E; }
.LBB0_188:
	s_abs_i32 s5, s94
	s_mul_hi_u32 s6, s5, s34
	s_mul_i32 s7, s6, s66
	s_sub_i32 s5, s5, s7
	s_ashr_i32 s4, s94, 31
	s_add_i32 s7, s6, 1
	s_sub_i32 s8, s5, s66
	s_cmp_ge_u32 s5, s66
	s_cselect_b32 s6, s7, s6
	s_cselect_b32 s5, s8, s5
	s_add_i32 s7, s6, 1
	s_cmp_ge_u32 s5, s66
	s_cselect_b32 s5, s7, s6
	s_xor_b32 s5, s5, s4
	s_sub_i32 s28, s5, s4
	s_mov_b64 s[4:5], s[0:1]
	s_load_dwordx2 s[6:7], s[4:5], 0x98
	s_mov_b64 s[4:5], s[0:1]
	s_load_dwordx2 s[8:9], s[4:5], 0x98
	s_mov_b64 s[4:5], s[0:1]
	s_load_dwordx2 s[74:75], s[4:5], 0x20
	s_mov_b64 s[4:5], s[0:1]
	s_load_dwordx2 s[76:77], s[4:5], 0x28
	s_mov_b64 s[4:5], s[0:1]
	s_load_dwordx2 s[70:71], s[4:5], 0x30
	s_mov_b64 s[4:5], s[0:1]
	s_load_dwordx2 s[72:73], s[4:5], 0x38
	s_mov_b64 s[4:5], s[0:1]
	s_load_dwordx2 s[68:69], s[4:5], 0x40
	s_mov_b64 s[4:5], s[0:1]
	v_mov_b32_e32 v202, v204
	s_mul_i32 s12, s28, s67
	s_ashr_i32 s13, s12, 31
	v_readfirstlane_b32 s15, v202
	s_and_b32 s16, s28, 7
	s_ashr_i32 s29, s15, 6
	s_lshl_b64 s[12:13], s[12:13], 15
	s_waitcnt lgkmcnt(0)
	s_add_u32 s8, s8, s12
	s_addc_u32 s9, s9, s13
	s_add_u32 s20, s8, 0x29b00000
	v_and_b32_e32 v209, 63, v202
	s_addc_u32 s8, s9, 0
	s_lshl_b32 s9, s15, 5
	s_and_b32 s21, s8, 0xffff
	s_lshl_b32 s8, s29, 10
	v_lshlrev_b32_e32 v0, 4, v209
	s_and_b32 s9, s9, 0xfffff000
	s_lshl_b32 s10, s29, 11
	v_or_b32_e32 v224, s8, v0
	s_and_b32 s10, s10, 0x800
	s_add_i32 s42, s8, 0
	s_add_i32 s8, s9, 0
	s_or_b32 s12, s9, s10
	s_mov_b32 m0, s42
	s_add_i32 s50, s42, 0x2000
	s_add_i32 s25, s8, s10
	s_addk_i32 s12, 0x4000
	buffer_load_dwordx4 v224, s[20:23], 0 offen lds
	s_mov_b32 m0, s50
	s_add_i32 s57, s25, 0x10000
	v_or_b32_e32 v223, s12, v0
	buffer_load_dwordx4 v224, s[20:23], s87 offen lds
	s_mov_b32 m0, s57
	s_add_i32 s99, s25, 0x10400
	buffer_load_dwordx4 v223, s[20:23], 0 offen lds
	s_mov_b32 m0, s99
	s_movk_i32 s8, 0x400
	s_add_i32 s54, s42, 0x4000
	buffer_load_dwordx4 v223, s[20:23], s8 offen lds
	s_mov_b32 m0, s54
	s_mov_b32 s9, 0x8000
	s_add_i32 s55, s42, 0x6000
	buffer_load_dwordx4 v224, s[20:23], s9 offen lds
	s_mov_b32 m0, s55
	s_mov_b32 s8, 0xa000
	s_add_i32 s30, s42, 0x8000
	buffer_load_dwordx4 v224, s[20:23], s8 offen lds
	s_mov_b32 m0, s30
	s_mov_b32 s8, 0x10000
	s_add_i32 s10, s42, 0xa000
	buffer_load_dwordx4 v224, s[20:23], s8 offen lds
	s_mov_b32 m0, s10
	s_mov_b32 s8, 0x12000
	s_add_i32 s39, s25, 0x14000
	buffer_load_dwordx4 v224, s[20:23], s8 offen lds
	s_mov_b32 m0, s39
	s_add_i32 s25, s25, 0x14400
	buffer_load_dwordx4 v223, s[20:23], s9 offen lds
	s_mov_b32 m0, s25
	s_mov_b32 s8, 0x8400
	buffer_load_dwordx4 v223, s[20:23], s8 offen lds
	s_cmp_eq_u32 s16, s100
	s_cbranch_scc1 .Ltab_skip
	s_mov_b32 s100, s16
	s_movk_i32 s8, 0x201
	v_cmp_gt_i32_e32 vcc, s8, v202
	s_and_saveexec_b64 s[8:9], vcc
	s_cbranch_execz .LBB0_206
	s_load_dwordx2 s[12:13], s[4:5], 0x88
	v_max_i32_e32 v0, 1, v202
	v_sub_u32_e32 v0, v0, v202
	v_add_u32_e32 v0, 0x1ff, v0
	s_movk_i32 s4, 0x1ff
	v_cmp_lt_u32_e32 vcc, s4, v0
	s_mov_b64 s[4:5], -1
	v_mov_b32_e32 v2, v202
	s_and_saveexec_b64 s[26:27], vcc
	s_cbranch_execz .LBB0_193
	v_lshrrev_b32_e32 v0, 9, v0
	v_add_u32_e32 v0, 1, v0
	v_and_b32_e32 v4, 0xfffffe, v0
	v_add_u32_e32 v203, 0x200, v202
	v_readlane_b32 s4, v246, 48
	s_mov_b32 s17, s16
	s_mov_b64 s[78:79], 0
	v_lshl_add_u32 v5, v202, 2, s4
	v_mov_b32_e32 v6, v4
	v_mov_b64_e32 v[2:3], v[202:203]

; #define LAS __attribute__((address_space(3)))
; #define NEAR_BIAS(C0, C1, k0v) do { if (!((((k0v) + 63 - qw0) <= -91) || (((k0v) - (qw0 + 31)) >= 91))) { const LAS float* tp_ = tab + ((k0v) + 4 * hi - (qw0 + r32) + 256);     \
;         _Pragma("unroll") for (int r = 0; r < 16; ++r) { C0[r] += tp_[(r & 3) + 8 * (r >> 2)]; C1[r] += tp_[(r & 3) + 8 * (r >> 2) + 32]; } } } while (0)
; #define SET_CINIT(k0v) do { const float ci_ = TILE_CB(k0v) - mhat; _Pragma("unroll") for (int r = 0; r < 16; ++r) cinit[r] = ci_; } while (0)
; __device__ __forceinline__ void attn_unit(LAS unsigned char* lds, bf16_t* Zg, const unsigned char* KVg, int S, int b, int h, int qb, const float* lq1, const float* lk1, const float* lq2, const float* lk2, const float* subln_g, const float* rel_bias, bool dostore = true) {
;     ...
;     bf16x8 qr[4];
;     { const bf16_t* qp = Zg + (rowbase + qw0 + r32) * ZLD + COL_Q + mp * 512 + h * 64 + hi * 8;
; #pragma unroll
;       for (int d0 = 0; d0 < 4; ++d0) qr[d0] = *(const bf16x8*)(qp + d0 * 16); }
;     asm volatile("s_waitcnt vmcnt(0)" ::: "memory");
;     __syncthreads();
;     const float c_neg = tab[0], c_pos = tab[512];
;     float mhat = 0.f, lsum = 0.f; f32x16 o[4]; o[0] = f32x16{}; o[1] = f32x16{}; o[2] = f32x16{}; o[3] = f32x16{};
;     const unsigned vlane = 65536 + (4 * hi + ((lane & 15) >> 2)) * 64 + ((lane >> 4) & 1) * 32 + (lane & 3) * 8;
;     unsigned kla[4];
; #pragma unroll
;     for (int d0 = 0; d0 < 4; ++d0) kla[d0] = mp * 8192 + r32 * 128 + (((2 * d0 + hi) ^ ((r32 >> 1) & 7)) << 4);
;     f32x16 cinit;
;     f32x16 pA0, pA1, pB0, pB1; u32x4 pw0, pw1, pw2, pw3;
;     ...
;     {
;         bf16x8 kf_[8]; const LAS unsigned char* kb_ = lds;
; #pragma unroll
;         for (int i_ = 0; i_ < 4; ++i_) { kf_[2 * i_] = *(const LAS bf16x8*)(kb_ + kla[i_]); kf_[2 * i_ + 1] = *(const LAS bf16x8*)(kb_ + kla[i_] + 4096); }
;         SET_CINIT(0);
; #pragma unroll
;         for (int i_ = 0; i_ < 8; ++i_) { if (i_ & 1) pA1 = __builtin_amdgcn_mfma_f32_32x32x16_bf16(kf_[i_], qr[i_ >> 1], (i_ < 2) ? cinit : pA1, 0, 0, 0);
;                                          else        pA0 = __builtin_amdgcn_mfma_f32_32x32x16_bf16(kf_[i_], qr[i_ >> 1], (i_ < 2) ? cinit : pA0, 0, 0, 0); }
;         NEAR_BIAS(pA0, pA1, 0);
.Ltab_skip:
	s_mul_i32 s4, s28, s66
	s_sub_i32 s4, s94, s4
	s_add_u32 s26, s6, 0x5a00000
	s_addc_u32 s27, s7, 0
	s_lshl_b32 s84, s29, 5
	s_ashr_i32 s82, s28, 3
	s_lshl_b32 s83, s4, 7
	s_and_b32 s85, s84, 0x60
	v_and_b32_e32 v210, 31, v202
	s_mul_hi_i32 s17, s82, s11
	s_mul_i32 s82, s82, s11
	s_or_b32 s78, s85, s83
	s_ashr_i32 s79, s78, 31
	v_or_b32_e32 v2, s82, v210
	v_mov_b32_e32 v3, s17
	v_lshl_add_u64 v[2:3], v[2:3], 0, s[78:79]
	v_mov_b64_e32 v[4:5], s[26:27]
	s_ashr_i32 s89, s15, 8
	v_mad_u64_u32 v[4:5], s[4:5], v2, s35, v[4:5]
	s_lshl_b32 s4, s89, 9
	v_mad_i32_i24 v5, v3, s35, v5
	s_ashr_i32 s5, s4, 31
	v_lshrrev_b32_e32 v38, 5, v209
	v_lshl_add_u64 v[2:3], s[4:5], 1, v[4:5]
	s_lshl_b32 s18, s16, 7
	v_lshl_add_u64 v[2:3], v[2:3], 0, s[18:19]
	v_lshlrev_b32_e32 v0, 4, v38
	v_lshl_add_u64 v[2:3], v[2:3], 0, v[0:1]
	global_load_dwordx4 v[190:193], v[2:3], off
	global_load_dwordx4 v[186:189], v[2:3], off offset:32
	global_load_dwordx4 v[178:181], v[2:3], off offset:64
	global_load_dwordx4 v[182:185], v[2:3], off offset:96
	v_lshrrev_b32_e32 v5, 1, v202
	v_lshlrev_b32_e32 v6, 7, v210
	v_bitop3_b32 v5, v38, v5, 7 bitop3:0x78
	v_lshl_or_b32 v39, s89, 13, v6
	v_readlane_b32 s4, v246, 48
	v_lshl_or_b32 v5, v5, 4, v39
	s_add_i32 s18, 0, 0x20000
	v_mov_b32_e32 v4, s4
	v_add_u32_e32 v216, 0, v5
	v_mov_b32_e32 v7, s18
	s_waitcnt vmcnt(0)
	s_waitcnt vmcnt(4) lgkmcnt(0)
	s_barrier
	ds_read_b32 v219, v4
	ds_read_b32 v218, v7
	ds_read_b128 v[34:37], v216
	s_cmpk_gt_i32 s78, 0x99
	s_cselect_b64 vcc, -1, 0
	s_cmpk_lt_i32 s78, 0xff87
	s_cselect_b64 s[4:5], -1, 0
	s_waitcnt lgkmcnt(2)
	v_cndmask_b32_e64 v2, 0, v219, s[4:5]
	s_waitcnt lgkmcnt(1)
	v_cndmask_b32_e32 v2, v2, v218, vcc
	v_mov_b32_e32 v3, v2
	v_mov_b32_e32 v4, v2
	v_mov_b32_e32 v5, v2
	v_mov_b32_e32 v6, v2
	v_mov_b32_e32 v7, v2
	v_mov_b32_e32 v8, v2
	v_mov_b32_e32 v9, v2
	v_mov_b32_e32 v10, v2
	v_mov_b32_e32 v11, v2
	v_mov_b32_e32 v12, v2
	v_mov_b32_e32 v13, v2
	v_mov_b32_e32 v14, v2
	v_mov_b32_e32 v15, v2
	v_mov_b32_e32 v16, v2
	v_mov_b32_e32 v17, v2
	v_bfe_u32 v40, v202, 1, 3
	v_bitop3_b32 v41, v38, v40, 2 bitop3:0x36
	v_lshl_or_b32 v41, v41, 4, v39
	v_add_u32_e32 v221, 0, v41
	v_bitop3_b32 v41, v38, v40, 4 bitop3:0x36
	v_lshl_or_b32 v41, v41, 4, v39
	v_add_u32_e32 v220, 0, v41
	v_bitop3_b32 v40, v38, v40, 6 bitop3:0x36
	v_lshl_or_b32 v39, v40, 4, v39
	v_add_u32_e32 v217, 0, v39
	s_add_i32 s4, s78, 0xffffff66
	v_lshlrev_b32_e32 v211, 2, v38
	s_cmp_gt_u32 s4, 0xfffffeec
	s_waitcnt vmcnt(3) lgkmcnt(0)
	v_mfma_f32_32x32x16_bf16 v[18:33], v[34:37], v[190:193], v[2:17]
	ds_read_b128 v[34:37], v216 offset:4096
	s_waitcnt lgkmcnt(0)
	v_mfma_f32_32x32x16_bf16 v[2:17], v[34:37], v[190:193], v[2:17]
	ds_read_b128 v[34:37], v221
	s_waitcnt vmcnt(2) lgkmcnt(0)
	v_mfma_f32_32x32x16_bf16 v[18:33], v[34:37], v[186:189], v[18:33]
	ds_read_b128 v[34:37], v221 offset:4096
	s_waitcnt lgkmcnt(0)
	v_mfma_f32_32x32x16_bf16 v[2:17], v[34:37], v[186:189], v[2:17]
	ds_read_b128 v[34:37], v220
	s_waitcnt vmcnt(1) lgkmcnt(0)
	v_mfma_f32_32x32x16_bf16 v[18:33], v[34:37], v[178:181], v[18:33]
	ds_read_b128 v[34:37], v220 offset:4096
	s_waitcnt lgkmcnt(0)
	v_mfma_f32_32x32x16_bf16 v[2:17], v[34:37], v[178:181], v[2:17]
	ds_read_b128 v[34:37], v217
	s_waitcnt vmcnt(0) lgkmcnt(0)
	v_mfma_f32_32x32x16_bf16 v[18:33], v[34:37], v[182:185], v[18:33]
	ds_read_b128 v[34:37], v217 offset:4096
	s_waitcnt lgkmcnt(0)
	v_mfma_f32_32x32x16_bf16 v[2:17], v[34:37], v[182:185], v[2:17]
	s_cbranch_scc0 .LBB0_208
	v_or_b32_e32 v34, s78, v210
	v_sub_u32_e32 v34, v211, v34
	v_lshl_add_u32 v62, v34, 2, s18
	v_add_u32_e32 v34, 0x400, v62
	v_add_u32_e32 v36, 0x480, v62
	ds_read2_b32 v[34:35], v34 offset1:1
	ds_read2_b32 v[36:37], v36 offset1:1
	v_add_u32_e32 v38, 0x408, v62
	v_add_u32_e32 v40, 0x488, v62
	v_add_u32_e32 v42, 0x420, v62
	v_add_u32_e32 v44, 0x4a0, v62
	v_add_u32_e32 v46, 0x428, v62
	v_add_u32_e32 v48, 0x4a8, v62
	v_add_u32_e32 v50, 0x440, v62
	v_add_u32_e32 v52, 0x4c0, v62
	v_add_u32_e32 v54, 0x448, v62
	v_add_u32_e32 v56, 0x4c8, v62
	v_add_u32_e32 v58, 0x460, v62
	v_add_u32_e32 v60, 0x4e0, v62
	v_add_u32_e32 v63, 0x468, v62
	v_add_u32_e32 v64, 0x4e8, v62
	ds_read2_b32 v[38:39], v38 offset1:1
	ds_read2_b32 v[40:41], v40 offset1:1
	ds_read2_b32 v[42:43], v42 offset1:1
	ds_read2_b32 v[44:45], v44 offset1:1
	ds_read2_b32 v[46:47], v46 offset1:1
	ds_read2_b32 v[48:49], v48 offset1:1
	ds_read2_b32 v[50:51], v50 offset1:1
	ds_read2_b32 v[52:53], v52 offset1:1
	ds_read2_b32 v[54:55], v54 offset1:1
	ds_read2_b32 v[56:57], v56 offset1:1
	ds_read2_b32 v[58:59], v58 offset1:1
	ds_read2_b32 v[60:61], v60 offset1:1
	ds_read2_b32 v[62:63], v63 offset1:1
	s_waitcnt lgkmcnt(14)
	v_pk_add_f32 v[18:19], v[18:19], v[34:35]
	ds_read2_b32 v[34:35], v64 offset1:1
	s_waitcnt lgkmcnt(3)
	v_pk_add_f32 v[30:31], v[30:31], v[58:59]
	v_pk_add_f32 v[28:29], v[28:29], v[54:55]
	s_waitcnt lgkmcnt(1)
	v_pk_add_f32 v[32:33], v[32:33], v[62:63]
	v_pk_add_f32 v[26:27], v[26:27], v[50:51]
	v_pk_add_f32 v[24:25], v[24:25], v[46:47]
	v_pk_add_f32 v[22:23], v[22:23], v[42:43]
	v_pk_add_f32 v[20:21], v[20:21], v[38:39]
	s_waitcnt lgkmcnt(0)
	v_pk_add_f32 v[16:17], v[16:17], v[34:35]
	v_pk_add_f32 v[14:15], v[14:15], v[60:61]
	v_pk_add_f32 v[12:13], v[12:13], v[56:57]
	v_pk_add_f32 v[10:11], v[10:11], v[52:53]
	v_pk_add_f32 v[8:9], v[8:9], v[48:49]
	v_pk_add_f32 v[6:7], v[6:7], v[44:45]
	v_pk_add_f32 v[4:5], v[4:5], v[40:41]
	v_pk_add_f32 v[2:3], v[2:3], v[36:37]

.LBB0_213:
	s_add_i32 s13, s93, 0xffff8000
	v_add_f32_e32 v228, v228, v0
	ds_read_b64_tr_b16 v[66:67], v226 offset:0
	ds_read_b64_tr_b16 v[68:69], v226 offset:512
	ds_read_b64_tr_b16 v[70:71], v226 offset:4096
	ds_read_b64_tr_b16 v[72:73], v226 offset:4608
	ds_read_b64_tr_b16 v[74:75], v226 offset:8192
	ds_read_b64_tr_b16 v[76:77], v226 offset:8704
	ds_read_b64_tr_b16 v[78:79], v226 offset:12288
	ds_read_b64_tr_b16 v[80:81], v226 offset:12800
	s_waitcnt lgkmcnt(6)
	s_nop 0
	s_add_i32 s12, s93, 0xffff8400
	v_mfma_f32_32x32x16_bf16 v[50:65], v[174:177], v[66:69], v[50:65]
	v_max3_f32 v0, v146, s92, v147
	v_exp_f32_e32 v146, v146
	v_exp_f32_e32 v147, v147
	s_add_i32 s29, s93, 0x2000
	ds_read_b64_tr_b16 v[66:67], v226 offset:1024
	ds_read_b64_tr_b16 v[68:69], v226 offset:1536
	s_waitcnt lgkmcnt(6)
	s_nop 0
	v_max3_f32 v0, v0, v148, v149
	v_mfma_f32_32x32x16_bf16 v[34:49], v[174:177], v[70:73], v[34:49]
	v_exp_f32_e32 v148, v148
	v_exp_f32_e32 v149, v149
	ds_read_b64_tr_b16 v[70:71], v226 offset:5120
	ds_read_b64_tr_b16 v[72:73], v226 offset:5632
	s_mov_b32 m0, s97
	s_waitcnt lgkmcnt(6)
	v_max3_f32 v0, v0, v150, v151
	buffer_load_dwordx4 v224, s[20:23], s93 offen lds
	v_mfma_f32_32x32x16_bf16 v[18:33], v[174:177], v[74:77], v[18:33]
	v_exp_f32_e32 v150, v150
	v_exp_f32_e32 v151, v151
	ds_read_b64_tr_b16 v[74:75], v226 offset:9216
	ds_read_b64_tr_b16 v[76:77], v226 offset:9728
	s_waitcnt lgkmcnt(6)
	s_nop 0
	v_max3_f32 v0, v0, v152, v153
	v_mfma_f32_32x32x16_bf16 v[2:17], v[174:177], v[78:81], v[2:17]
	v_exp_f32_e32 v152, v152
	v_exp_f32_e32 v153, v153
	ds_read_b64_tr_b16 v[78:79], v226 offset:13312
	ds_read_b64_tr_b16 v[80:81], v226 offset:13824
	s_waitcnt lgkmcnt(6)
	s_nop 0
	v_max3_f32 v0, v0, v154, v155
	v_mfma_f32_32x32x16_bf16 v[50:65], v[170:173], v[66:69], v[50:65]
	v_exp_f32_e32 v154, v154
	v_exp_f32_e32 v155, v155
	ds_read_b64_tr_b16 v[66:67], v226 offset:2048
	ds_read_b64_tr_b16 v[68:69], v226 offset:2560
	s_mov_b32 m0, s51
	s_waitcnt lgkmcnt(6)
	v_max3_f32 v0, v0, v156, v157
	buffer_load_dwordx4 v224, s[20:23], s29 offen lds
	v_mfma_f32_32x32x16_bf16 v[34:49], v[170:173], v[70:73], v[34:49]
	v_exp_f32_e32 v156, v156
	v_exp_f32_e32 v157, v157
	ds_read_b64_tr_b16 v[70:71], v226 offset:6144
	ds_read_b64_tr_b16 v[72:73], v226 offset:6656
	s_waitcnt lgkmcnt(6)
	s_nop 0
	v_max3_f32 v0, v0, v158, v159
	v_mfma_f32_32x32x16_bf16 v[18:33], v[170:173], v[74:77], v[18:33]
	v_exp_f32_e32 v158, v158
	v_exp_f32_e32 v159, v159
	ds_read_b64_tr_b16 v[74:75], v226 offset:10240
	ds_read_b64_tr_b16 v[76:77], v226 offset:10752
	s_waitcnt lgkmcnt(6)
	s_nop 0
	v_max3_f32 v0, v0, v160, v161
	v_mfma_f32_32x32x16_bf16 v[2:17], v[170:173], v[78:81], v[2:17]
	v_exp_f32_e32 v160, v160
	v_exp_f32_e32 v161, v161
	ds_read_b64_tr_b16 v[78:79], v226 offset:14336
	ds_read_b64_tr_b16 v[80:81], v226 offset:14848
	s_mov_b32 m0, s31
	s_waitcnt lgkmcnt(6)
	v_max3_f32 v0, v0, v130, v131
	buffer_load_dwordx4 v223, s[20:23], s13 offen lds
	v_mfma_f32_32x32x16_bf16 v[50:65], v[166:169], v[66:69], v[50:65]
	v_exp_f32_e32 v130, v130
	v_exp_f32_e32 v131, v131
	ds_read_b64_tr_b16 v[66:67], v226 offset:3072
	ds_read_b64_tr_b16 v[68:69], v226 offset:3584
	s_waitcnt lgkmcnt(6)
	s_nop 0
	v_max3_f32 v0, v0, v132, v133
	v_mfma_f32_32x32x16_bf16 v[34:49], v[166:169], v[70:73], v[34:49]
	v_exp_f32_e32 v132, v132
	v_exp_f32_e32 v133, v133
	ds_read_b64_tr_b16 v[70:71], v226 offset:7168
	ds_read_b64_tr_b16 v[72:73], v226 offset:7680
	s_waitcnt lgkmcnt(6)
	s_nop 0
	v_max3_f32 v0, v0, v134, v135
	v_mfma_f32_32x32x16_bf16 v[18:33], v[166:169], v[74:77], v[18:33]
	v_exp_f32_e32 v134, v134
	v_exp_f32_e32 v135, v135
	ds_read_b64_tr_b16 v[74:75], v226 offset:11264
	ds_read_b64_tr_b16 v[76:77], v226 offset:11776
	s_mov_b32 m0, s91
	s_waitcnt lgkmcnt(6)
	v_max3_f32 v0, v0, v136, v137
	buffer_load_dwordx4 v223, s[20:23], s12 offen lds
	v_mfma_f32_32x32x16_bf16 v[2:17], v[166:169], v[78:81], v[2:17]
	v_exp_f32_e32 v136, v136
	v_exp_f32_e32 v137, v137
	ds_read_b64_tr_b16 v[78:79], v226 offset:15360
	ds_read_b64_tr_b16 v[80:81], v226 offset:15872
	s_waitcnt lgkmcnt(6)
	s_nop 0
	v_max3_f32 v0, v0, v138, v139
	v_mfma_f32_32x32x16_bf16 v[50:65], v[162:165], v[66:69], v[50:65]
	v_exp_f32_e32 v138, v138
	v_exp_f32_e32 v139, v139
	s_waitcnt lgkmcnt(4)
	s_nop 0
	v_max3_f32 v0, v0, v140, v141
	v_mfma_f32_32x32x16_bf16 v[34:49], v[162:165], v[70:73], v[34:49]
	v_exp_f32_e32 v140, v140
	v_exp_f32_e32 v141, v141
	s_waitcnt lgkmcnt(2)
	s_nop 0
	v_max3_f32 v0, v0, v142, v143
	v_mfma_f32_32x32x16_bf16 v[18:33], v[162:165], v[74:77], v[18:33]
	v_exp_f32_e32 v142, v142
	v_exp_f32_e32 v143, v143
	s_waitcnt lgkmcnt(0)
	s_nop 0
	v_max3_f32 v0, v0, v144, v145
	v_mfma_f32_32x32x16_bf16 v[2:17], v[162:165], v[78:81], v[2:17]
	v_exp_f32_e32 v144, v144
	v_exp_f32_e32 v145, v145
	s_nop 0
	v_mov_b32_e32 v66, v0
	s_nop 1
	v_permlane32_swap_b32_e32 v0, v66
	v_max_f32_e32 v0, v0, v66
	v_cmp_lt_f32_e32 vcc, s33, v0
	s_cmp_eq_u64 vcc, 0
	s_cselect_b64 s[12:13], -1, 0
	s_cbranch_vccz .LBB0_217
	v_max_f32_e32 v0, v0, v0
	v_max_f32_e32 v66, 0, v0
	v_exp_f32_e64 v0, -v66
	s_and_saveexec_b64 s[80:81], s[4:5]
	ds_write_b32 v213, v0
	s_or_b64 exec, exec, s[80:81]
	s_waitcnt lgkmcnt(0)
	v_add_f32_e32 v222, v222, v66
	ds_read_b128 v[66:69], v212
	ds_read_b128 v[70:73], v212 offset:32
	ds_read_b128 v[74:77], v212 offset:64
	ds_read_b128 v[78:81], v212 offset:96
	v_mul_f32_e32 v228, v228, v0
	s_waitcnt lgkmcnt(3)
	v_pk_mul_f32 v[52:53], v[52:53], v[68:69]
	s_waitcnt lgkmcnt(2)
	v_pk_mul_f32 v[56:57], v[56:57], v[72:73]
	s_waitcnt lgkmcnt(1)
	v_pk_mul_f32 v[60:61], v[60:61], v[76:77]
	s_waitcnt lgkmcnt(0)
	v_pk_mul_f32 v[64:65], v[64:65], v[80:81]
	v_pk_mul_f32 v[62:63], v[62:63], v[78:79]
	v_pk_mul_f32 v[58:59], v[58:59], v[74:75]
	v_pk_mul_f32 v[54:55], v[54:55], v[70:71]
	v_pk_mul_f32 v[50:51], v[50:51], v[66:67]
	v_pk_mul_f32 v[48:49], v[48:49], v[80:81]
	v_pk_mul_f32 v[44:45], v[44:45], v[76:77]
	v_pk_mul_f32 v[40:41], v[40:41], v[72:73]
	v_pk_mul_f32 v[36:37], v[36:37], v[68:69]
	v_pk_mul_f32 v[46:47], v[46:47], v[78:79]
	v_pk_mul_f32 v[42:43], v[42:43], v[74:75]
	v_pk_mul_f32 v[38:39], v[38:39], v[70:71]
	v_pk_mul_f32 v[34:35], v[34:35], v[66:67]
	v_pk_mul_f32 v[32:33], v[32:33], v[80:81]
	v_pk_mul_f32 v[28:29], v[28:29], v[76:77]
	v_pk_mul_f32 v[24:25], v[24:25], v[72:73]
	v_pk_mul_f32 v[20:21], v[20:21], v[68:69]
	v_pk_mul_f32 v[30:31], v[30:31], v[78:79]
	v_pk_mul_f32 v[26:27], v[26:27], v[74:75]
	v_pk_mul_f32 v[22:23], v[22:23], v[70:71]
	v_pk_mul_f32 v[18:19], v[18:19], v[66:67]
	v_pk_mul_f32 v[16:17], v[16:17], v[80:81]
	v_pk_mul_f32 v[12:13], v[12:13], v[76:77]
	v_pk_mul_f32 v[8:9], v[8:9], v[72:73]
	v_pk_mul_f32 v[4:5], v[4:5], v[68:69]
	v_pk_mul_f32 v[14:15], v[14:15], v[78:79]
	v_pk_mul_f32 v[10:11], v[10:11], v[74:75]
	v_pk_mul_f32 v[6:7], v[6:7], v[70:71]
	v_pk_mul_f32 v[2:3], v[2:3], v[66:67]
	v_pk_mul_f32 v[160:161], v[160:161], v[0:1] op_sel_hi:[1,0]
	v_pk_mul_f32 v[158:159], v[158:159], v[0:1] op_sel_hi:[1,0]
	v_pk_mul_f32 v[156:157], v[156:157], v[0:1] op_sel_hi:[1,0]
	v_pk_mul_f32 v[154:155], v[154:155], v[0:1] op_sel_hi:[1,0]
	v_pk_mul_f32 v[152:153], v[152:153], v[0:1] op_sel_hi:[1,0]
	v_pk_mul_f32 v[150:151], v[150:151], v[0:1] op_sel_hi:[1,0]
	v_pk_mul_f32 v[148:149], v[148:149], v[0:1] op_sel_hi:[1,0]
	v_pk_mul_f32 v[146:147], v[146:147], v[0:1] op_sel_hi:[1,0]
	v_pk_mul_f32 v[144:145], v[144:145], v[0:1] op_sel_hi:[1,0]
	v_pk_mul_f32 v[142:143], v[142:143], v[0:1] op_sel_hi:[1,0]
	v_pk_mul_f32 v[140:141], v[140:141], v[0:1] op_sel_hi:[1,0]
	v_pk_mul_f32 v[138:139], v[138:139], v[0:1] op_sel_hi:[1,0]
	v_pk_mul_f32 v[136:137], v[136:137], v[0:1] op_sel_hi:[1,0]
	v_pk_mul_f32 v[134:135], v[134:135], v[0:1] op_sel_hi:[1,0]
	v_pk_mul_f32 v[132:133], v[132:133], v[0:1] op_sel_hi:[1,0]
	v_pk_mul_f32 v[130:131], v[130:131], v[0:1] op_sel_hi:[1,0]

.LBB0_222:
	v_add_f32_e32 v228, v228, v0
	ds_read_b64_tr_b16 v[130:131], v225 offset:0
	ds_read_b64_tr_b16 v[132:133], v225 offset:512
	ds_read_b64_tr_b16 v[134:135], v225 offset:4096
	ds_read_b64_tr_b16 v[136:137], v225 offset:4608
	ds_read_b64_tr_b16 v[138:139], v225 offset:8192
	ds_read_b64_tr_b16 v[140:141], v225 offset:8704
	ds_read_b64_tr_b16 v[142:143], v225 offset:12288
	ds_read_b64_tr_b16 v[144:145], v225 offset:12800
	s_waitcnt lgkmcnt(6)
	s_nop 0
	v_max3_f32 v0, v114, s92, v115
	v_mfma_f32_32x32x16_bf16 v[50:65], v[174:177], v[130:133], v[50:65]
	v_exp_f32_e32 v114, v114
	v_exp_f32_e32 v115, v115
	ds_read_b64_tr_b16 v[130:131], v225 offset:1024
	ds_read_b64_tr_b16 v[132:133], v225 offset:1536
	s_waitcnt lgkmcnt(6)
	s_nop 0
	v_max3_f32 v0, v0, v116, v117
	v_mfma_f32_32x32x16_bf16 v[34:49], v[174:177], v[134:137], v[34:49]
	v_exp_f32_e32 v116, v116
	v_exp_f32_e32 v117, v117
	ds_read_b64_tr_b16 v[134:135], v225 offset:5120
	ds_read_b64_tr_b16 v[136:137], v225 offset:5632
	s_waitcnt lgkmcnt(6)
	s_nop 0
	v_max3_f32 v0, v0, v118, v119
	v_mfma_f32_32x32x16_bf16 v[18:33], v[174:177], v[138:141], v[18:33]
	v_exp_f32_e32 v118, v118
	v_exp_f32_e32 v119, v119
	ds_read_b64_tr_b16 v[138:139], v225 offset:9216
	ds_read_b64_tr_b16 v[140:141], v225 offset:9728
	s_waitcnt lgkmcnt(6)
	s_nop 0
	v_max3_f32 v0, v0, v120, v121
	v_mfma_f32_32x32x16_bf16 v[2:17], v[174:177], v[142:145], v[2:17]
	v_exp_f32_e32 v120, v120
	v_exp_f32_e32 v121, v121
	ds_read_b64_tr_b16 v[142:143], v225 offset:13312
	ds_read_b64_tr_b16 v[144:145], v225 offset:13824
	s_waitcnt lgkmcnt(6)
	s_nop 0
	v_max3_f32 v0, v0, v122, v123
	v_mfma_f32_32x32x16_bf16 v[50:65], v[170:173], v[130:133], v[50:65]
	v_exp_f32_e32 v122, v122
	v_exp_f32_e32 v123, v123
	ds_read_b64_tr_b16 v[130:131], v225 offset:2048
	ds_read_b64_tr_b16 v[132:133], v225 offset:2560
	s_waitcnt lgkmcnt(6)
	s_nop 0
	v_max3_f32 v0, v0, v124, v125
	v_mfma_f32_32x32x16_bf16 v[34:49], v[170:173], v[134:137], v[34:49]
	v_exp_f32_e32 v124, v124
	v_exp_f32_e32 v125, v125
	ds_read_b64_tr_b16 v[134:135], v225 offset:6144
	ds_read_b64_tr_b16 v[136:137], v225 offset:6656
	s_waitcnt lgkmcnt(6)
	s_nop 0
	v_max3_f32 v0, v0, v126, v127
	v_mfma_f32_32x32x16_bf16 v[18:33], v[170:173], v[138:141], v[18:33]
	v_exp_f32_e32 v126, v126
	v_exp_f32_e32 v127, v127
	ds_read_b64_tr_b16 v[138:139], v225 offset:10240
	ds_read_b64_tr_b16 v[140:141], v225 offset:10752
	s_waitcnt lgkmcnt(6)
	s_nop 0
	v_max3_f32 v0, v0, v128, v129
	v_mfma_f32_32x32x16_bf16 v[2:17], v[170:173], v[142:145], v[2:17]
	v_exp_f32_e32 v128, v128
	v_exp_f32_e32 v129, v129
	ds_read_b64_tr_b16 v[142:143], v225 offset:14336
	ds_read_b64_tr_b16 v[144:145], v225 offset:14848
	s_waitcnt lgkmcnt(6)
	s_nop 0
	v_max3_f32 v0, v0, v98, v99
	v_mfma_f32_32x32x16_bf16 v[50:65], v[166:169], v[130:133], v[50:65]
	v_exp_f32_e32 v98, v98
	v_exp_f32_e32 v99, v99
	ds_read_b64_tr_b16 v[130:131], v225 offset:3072
	ds_read_b64_tr_b16 v[132:133], v225 offset:3584
	s_waitcnt lgkmcnt(6)
	s_nop 0
	v_max3_f32 v0, v0, v100, v101
	v_mfma_f32_32x32x16_bf16 v[34:49], v[166:169], v[134:137], v[34:49]
	v_exp_f32_e32 v100, v100
	v_exp_f32_e32 v101, v101
	ds_read_b64_tr_b16 v[134:135], v225 offset:7168
	ds_read_b64_tr_b16 v[136:137], v225 offset:7680
	s_waitcnt lgkmcnt(6)
	s_nop 0
	v_max3_f32 v0, v0, v102, v103
	v_mfma_f32_32x32x16_bf16 v[18:33], v[166:169], v[138:141], v[18:33]
	v_exp_f32_e32 v102, v102
	v_exp_f32_e32 v103, v103
	ds_read_b64_tr_b16 v[138:139], v225 offset:11264
	ds_read_b64_tr_b16 v[140:141], v225 offset:11776
	s_waitcnt lgkmcnt(6)
	s_nop 0
	v_max3_f32 v0, v0, v104, v105
	v_mfma_f32_32x32x16_bf16 v[2:17], v[166:169], v[142:145], v[2:17]
	v_exp_f32_e32 v104, v104
	v_exp_f32_e32 v105, v105
	ds_read_b64_tr_b16 v[142:143], v225 offset:15360
	ds_read_b64_tr_b16 v[144:145], v225 offset:15872
	s_waitcnt lgkmcnt(6)
	s_nop 0
	v_max3_f32 v0, v0, v106, v107
	v_mfma_f32_32x32x16_bf16 v[50:65], v[162:165], v[130:133], v[50:65]
	v_exp_f32_e32 v106, v106
	v_exp_f32_e32 v107, v107
	s_waitcnt lgkmcnt(4)
	s_nop 0
	v_max3_f32 v0, v0, v108, v109
	v_mfma_f32_32x32x16_bf16 v[34:49], v[162:165], v[134:137], v[34:49]
	v_exp_f32_e32 v108, v108
	v_exp_f32_e32 v109, v109
	s_waitcnt lgkmcnt(2)
	s_nop 0
	v_max3_f32 v0, v0, v110, v111
	v_mfma_f32_32x32x16_bf16 v[18:33], v[162:165], v[138:141], v[18:33]
	v_exp_f32_e32 v110, v110
	v_exp_f32_e32 v111, v111
	s_waitcnt lgkmcnt(0)
	s_nop 0
	v_max3_f32 v0, v0, v112, v113
	v_mfma_f32_32x32x16_bf16 v[2:17], v[162:165], v[142:145], v[2:17]
	v_exp_f32_e32 v112, v112
	v_exp_f32_e32 v113, v113
	s_nop 0
	v_mov_b32_e32 v130, v0
	s_nop 1
	v_permlane32_swap_b32_e32 v0, v130
	v_max_f32_e32 v0, v0, v130
	v_cmp_lt_f32_e32 vcc, s33, v0
	s_cmp_eq_u64 vcc, 0
	s_cselect_b64 s[12:13], -1, 0
	s_cbranch_vccnz .LBB0_240
	s_andn2_b64 vcc, exec, s[12:13]
	s_mov_b64 s[12:13], -1
	s_cbranch_vccz .LBB0_243

.LBB0_228:
	s_add_i32 s65, s93, 0x10000
	v_add_f32_e32 v228, v228, v0
	ds_read_b64_tr_b16 v[98:99], v215 offset:0
	ds_read_b64_tr_b16 v[100:101], v215 offset:512
	ds_read_b64_tr_b16 v[102:103], v215 offset:4096
	ds_read_b64_tr_b16 v[104:105], v215 offset:4608
	ds_read_b64_tr_b16 v[106:107], v215 offset:8192
	ds_read_b64_tr_b16 v[108:109], v215 offset:8704
	ds_read_b64_tr_b16 v[110:111], v215 offset:12288
	ds_read_b64_tr_b16 v[112:113], v215 offset:12800
	s_waitcnt lgkmcnt(6)
	s_nop 0
	s_add_i32 s12, s93, 0x8400
	v_mfma_f32_32x32x16_bf16 v[50:65], v[174:177], v[98:101], v[50:65]
	s_add_i32 s13, s93, 0x12000
	v_max3_f32 v0, v146, s92, v147
	v_exp_f32_e32 v146, v146
	v_exp_f32_e32 v147, v147
	ds_read_b64_tr_b16 v[98:99], v215 offset:1024
	ds_read_b64_tr_b16 v[100:101], v215 offset:1536
	s_waitcnt lgkmcnt(6)
	s_nop 0
	v_max3_f32 v0, v0, v148, v149
	v_mfma_f32_32x32x16_bf16 v[34:49], v[174:177], v[102:105], v[34:49]
	v_exp_f32_e32 v148, v148
	v_exp_f32_e32 v149, v149
	ds_read_b64_tr_b16 v[102:103], v215 offset:5120
	ds_read_b64_tr_b16 v[104:105], v215 offset:5632
	s_mov_b32 m0, s54
	s_waitcnt lgkmcnt(6)
	v_max3_f32 v0, v0, v150, v151
	buffer_load_dwordx4 v224, s[20:23], s65 offen lds
	v_mfma_f32_32x32x16_bf16 v[18:33], v[174:177], v[106:109], v[18:33]
	v_exp_f32_e32 v150, v150
	v_exp_f32_e32 v151, v151
	ds_read_b64_tr_b16 v[106:107], v215 offset:9216
	ds_read_b64_tr_b16 v[108:109], v215 offset:9728
	s_waitcnt lgkmcnt(6)
	s_nop 0
	v_max3_f32 v0, v0, v152, v153
	v_mfma_f32_32x32x16_bf16 v[2:17], v[174:177], v[110:113], v[2:17]
	v_exp_f32_e32 v152, v152
	v_exp_f32_e32 v153, v153
	ds_read_b64_tr_b16 v[110:111], v215 offset:13312
	ds_read_b64_tr_b16 v[112:113], v215 offset:13824
	s_waitcnt lgkmcnt(6)
	s_nop 0
	v_max3_f32 v0, v0, v154, v155
	v_mfma_f32_32x32x16_bf16 v[50:65], v[170:173], v[98:101], v[50:65]
	v_exp_f32_e32 v154, v154
	v_exp_f32_e32 v155, v155
	ds_read_b64_tr_b16 v[98:99], v215 offset:2048
	ds_read_b64_tr_b16 v[100:101], v215 offset:2560
	s_mov_b32 m0, s55
	s_waitcnt lgkmcnt(6)
	v_max3_f32 v0, v0, v156, v157
	buffer_load_dwordx4 v224, s[20:23], s13 offen lds
	v_mfma_f32_32x32x16_bf16 v[34:49], v[170:173], v[102:105], v[34:49]
	v_exp_f32_e32 v156, v156
	v_exp_f32_e32 v157, v157
	ds_read_b64_tr_b16 v[102:103], v215 offset:6144
	ds_read_b64_tr_b16 v[104:105], v215 offset:6656
	s_waitcnt lgkmcnt(6)
	s_nop 0
	v_max3_f32 v0, v0, v158, v159
	v_mfma_f32_32x32x16_bf16 v[18:33], v[170:173], v[106:109], v[18:33]
	v_exp_f32_e32 v158, v158
	v_exp_f32_e32 v159, v159
	ds_read_b64_tr_b16 v[106:107], v215 offset:10240
	ds_read_b64_tr_b16 v[108:109], v215 offset:10752
	s_waitcnt lgkmcnt(6)
	s_nop 0
	v_max3_f32 v0, v0, v160, v161
	v_mfma_f32_32x32x16_bf16 v[2:17], v[170:173], v[110:113], v[2:17]
	v_exp_f32_e32 v160, v160
	v_exp_f32_e32 v161, v161
	ds_read_b64_tr_b16 v[110:111], v215 offset:14336
	ds_read_b64_tr_b16 v[112:113], v215 offset:14848
	s_mov_b32 m0, s57
	s_waitcnt lgkmcnt(6)
	v_max3_f32 v0, v0, v130, v131
	buffer_load_dwordx4 v223, s[20:23], s64 offen lds
	v_mfma_f32_32x32x16_bf16 v[50:65], v[166:169], v[98:101], v[50:65]
	v_exp_f32_e32 v130, v130
	v_exp_f32_e32 v131, v131
	ds_read_b64_tr_b16 v[98:99], v215 offset:3072
	ds_read_b64_tr_b16 v[100:101], v215 offset:3584
	s_waitcnt lgkmcnt(6)
	s_nop 0
	v_max3_f32 v0, v0, v132, v133
	v_mfma_f32_32x32x16_bf16 v[34:49], v[166:169], v[102:105], v[34:49]
	v_exp_f32_e32 v132, v132
	v_exp_f32_e32 v133, v133
	ds_read_b64_tr_b16 v[102:103], v215 offset:7168
	ds_read_b64_tr_b16 v[104:105], v215 offset:7680
	s_waitcnt lgkmcnt(6)
	s_nop 0
	v_max3_f32 v0, v0, v134, v135
	v_mfma_f32_32x32x16_bf16 v[18:33], v[166:169], v[106:109], v[18:33]
	v_exp_f32_e32 v134, v134
	v_exp_f32_e32 v135, v135
	ds_read_b64_tr_b16 v[106:107], v215 offset:11264
	ds_read_b64_tr_b16 v[108:109], v215 offset:11776
	s_mov_b32 m0, s99
	s_waitcnt lgkmcnt(6)
	v_max3_f32 v0, v0, v136, v137
	buffer_load_dwordx4 v223, s[20:23], s12 offen lds
	v_mfma_f32_32x32x16_bf16 v[2:17], v[166:169], v[110:113], v[2:17]
	v_exp_f32_e32 v136, v136
	v_exp_f32_e32 v137, v137
	ds_read_b64_tr_b16 v[110:111], v215 offset:15360
	ds_read_b64_tr_b16 v[112:113], v215 offset:15872
	s_waitcnt lgkmcnt(6)
	s_nop 0
	v_max3_f32 v0, v0, v138, v139
	v_mfma_f32_32x32x16_bf16 v[50:65], v[162:165], v[98:101], v[50:65]
	v_exp_f32_e32 v138, v138
	v_exp_f32_e32 v139, v139
	s_waitcnt lgkmcnt(4)
	s_nop 0
	v_max3_f32 v0, v0, v140, v141
	v_mfma_f32_32x32x16_bf16 v[34:49], v[162:165], v[102:105], v[34:49]
	v_exp_f32_e32 v140, v140
	v_exp_f32_e32 v141, v141
	s_waitcnt lgkmcnt(2)
	s_nop 0
	v_max3_f32 v0, v0, v142, v143
	v_mfma_f32_32x32x16_bf16 v[18:33], v[162:165], v[106:109], v[18:33]
	v_exp_f32_e32 v142, v142
	v_exp_f32_e32 v143, v143
	s_waitcnt lgkmcnt(0)
	s_nop 0
	v_max3_f32 v0, v0, v144, v145
	v_mfma_f32_32x32x16_bf16 v[2:17], v[162:165], v[110:113], v[2:17]
	v_exp_f32_e32 v144, v144
	v_exp_f32_e32 v145, v145
	s_nop 0
	v_mov_b32_e32 v98, v0
	s_nop 1
	v_permlane32_swap_b32_e32 v0, v98
	v_max_f32_e32 v0, v0, v98
	v_cmp_lt_f32_e32 vcc, s33, v0
	s_cmp_eq_u64 vcc, 0
	s_cselect_b64 s[12:13], -1, 0
	s_cbranch_vccnz .LBB0_244
	s_andn2_b64 vcc, exec, s[12:13]
	s_mov_b64 s[12:13], -1
	s_cbranch_vccz .LBB0_247

.LBB0_234:
	v_add_f32_e32 v228, v228, v0
	ds_read_b64_tr_b16 v[130:131], v214 offset:0
	ds_read_b64_tr_b16 v[132:133], v214 offset:512
	ds_read_b64_tr_b16 v[134:135], v214 offset:4096
	ds_read_b64_tr_b16 v[136:137], v214 offset:4608
	ds_read_b64_tr_b16 v[138:139], v214 offset:8192
	ds_read_b64_tr_b16 v[140:141], v214 offset:8704
	ds_read_b64_tr_b16 v[142:143], v214 offset:12288
	ds_read_b64_tr_b16 v[144:145], v214 offset:12800
	s_waitcnt lgkmcnt(6)
	s_nop 0
	v_max3_f32 v0, v114, s92, v115
	v_mfma_f32_32x32x16_bf16 v[50:65], v[174:177], v[130:133], v[50:65]
	v_exp_f32_e32 v114, v114
	v_exp_f32_e32 v115, v115
	ds_read_b64_tr_b16 v[130:131], v214 offset:1024
	ds_read_b64_tr_b16 v[132:133], v214 offset:1536
	s_waitcnt lgkmcnt(6)
	s_nop 0
	v_max3_f32 v0, v0, v116, v117
	v_mfma_f32_32x32x16_bf16 v[34:49], v[174:177], v[134:137], v[34:49]
	v_exp_f32_e32 v116, v116
	v_exp_f32_e32 v117, v117
	ds_read_b64_tr_b16 v[134:135], v214 offset:5120
	ds_read_b64_tr_b16 v[136:137], v214 offset:5632
	s_waitcnt lgkmcnt(6)
	s_nop 0
	v_max3_f32 v0, v0, v118, v119
	v_mfma_f32_32x32x16_bf16 v[18:33], v[174:177], v[138:141], v[18:33]
	v_exp_f32_e32 v118, v118
	v_exp_f32_e32 v119, v119
	ds_read_b64_tr_b16 v[138:139], v214 offset:9216
	ds_read_b64_tr_b16 v[140:141], v214 offset:9728
	s_waitcnt lgkmcnt(6)
	s_nop 0
	v_max3_f32 v0, v0, v120, v121
	v_mfma_f32_32x32x16_bf16 v[2:17], v[174:177], v[142:145], v[2:17]
	v_exp_f32_e32 v120, v120
	v_exp_f32_e32 v121, v121
	ds_read_b64_tr_b16 v[142:143], v214 offset:13312
	ds_read_b64_tr_b16 v[144:145], v214 offset:13824
	s_waitcnt lgkmcnt(6)
	s_nop 0
	v_max3_f32 v0, v0, v122, v123
	v_mfma_f32_32x32x16_bf16 v[50:65], v[170:173], v[130:133], v[50:65]
	v_exp_f32_e32 v122, v122
	v_exp_f32_e32 v123, v123
	ds_read_b64_tr_b16 v[130:131], v214 offset:2048
	ds_read_b64_tr_b16 v[132:133], v214 offset:2560
	s_waitcnt lgkmcnt(6)
	s_nop 0
	v_max3_f32 v0, v0, v124, v125
	v_mfma_f32_32x32x16_bf16 v[34:49], v[170:173], v[134:137], v[34:49]
	v_exp_f32_e32 v124, v124
	v_exp_f32_e32 v125, v125
	ds_read_b64_tr_b16 v[134:135], v214 offset:6144
	ds_read_b64_tr_b16 v[136:137], v214 offset:6656
	s_waitcnt lgkmcnt(6)
	s_nop 0
	v_max3_f32 v0, v0, v126, v127
	v_mfma_f32_32x32x16_bf16 v[18:33], v[170:173], v[138:141], v[18:33]
	v_exp_f32_e32 v126, v126
	v_exp_f32_e32 v127, v127
	ds_read_b64_tr_b16 v[138:139], v214 offset:10240
	ds_read_b64_tr_b16 v[140:141], v214 offset:10752
	s_waitcnt lgkmcnt(6)
	s_nop 0
	v_max3_f32 v0, v0, v128, v129
	v_mfma_f32_32x32x16_bf16 v[2:17], v[170:173], v[142:145], v[2:17]
	v_exp_f32_e32 v128, v128
	v_exp_f32_e32 v129, v129
	ds_read_b64_tr_b16 v[142:143], v214 offset:14336
	ds_read_b64_tr_b16 v[144:145], v214 offset:14848
	s_waitcnt lgkmcnt(6)
	s_nop 0
	v_max3_f32 v0, v0, v98, v99
	v_mfma_f32_32x32x16_bf16 v[50:65], v[166:169], v[130:133], v[50:65]
	v_exp_f32_e32 v98, v98
	v_exp_f32_e32 v99, v99
	ds_read_b64_tr_b16 v[130:131], v214 offset:3072
	ds_read_b64_tr_b16 v[132:133], v214 offset:3584
	s_waitcnt lgkmcnt(6)
	s_nop 0
	v_max3_f32 v0, v0, v100, v101
	v_mfma_f32_32x32x16_bf16 v[34:49], v[166:169], v[134:137], v[34:49]
	v_exp_f32_e32 v100, v100
	v_exp_f32_e32 v101, v101
	ds_read_b64_tr_b16 v[134:135], v214 offset:7168
	ds_read_b64_tr_b16 v[136:137], v214 offset:7680
	s_waitcnt lgkmcnt(6)
	s_nop 0
	v_max3_f32 v0, v0, v102, v103
	v_mfma_f32_32x32x16_bf16 v[18:33], v[166:169], v[138:141], v[18:33]
	v_exp_f32_e32 v102, v102
	v_exp_f32_e32 v103, v103
	ds_read_b64_tr_b16 v[138:139], v214 offset:11264
	ds_read_b64_tr_b16 v[140:141], v214 offset:11776
	s_waitcnt lgkmcnt(6)
	s_nop 0
	v_max3_f32 v0, v0, v104, v105
	v_mfma_f32_32x32x16_bf16 v[2:17], v[166:169], v[142:145], v[2:17]
	v_exp_f32_e32 v104, v104
	v_exp_f32_e32 v105, v105
	ds_read_b64_tr_b16 v[142:143], v214 offset:15360
	ds_read_b64_tr_b16 v[144:145], v214 offset:15872
	s_waitcnt lgkmcnt(6)
	s_nop 0
	v_max3_f32 v0, v0, v106, v107
	v_mfma_f32_32x32x16_bf16 v[50:65], v[162:165], v[130:133], v[50:65]
	v_exp_f32_e32 v106, v106
	v_exp_f32_e32 v107, v107
	s_waitcnt lgkmcnt(4)
	s_nop 0
	v_max3_f32 v0, v0, v108, v109
	v_mfma_f32_32x32x16_bf16 v[34:49], v[162:165], v[134:137], v[34:49]
	v_exp_f32_e32 v108, v108
	v_exp_f32_e32 v109, v109
	s_waitcnt lgkmcnt(2)
	s_nop 0
	v_max3_f32 v0, v0, v110, v111
	v_mfma_f32_32x32x16_bf16 v[18:33], v[162:165], v[138:141], v[18:33]
	v_exp_f32_e32 v110, v110
	v_exp_f32_e32 v111, v111
	s_waitcnt lgkmcnt(0)
	s_nop 0
	v_max3_f32 v0, v0, v112, v113
	v_mfma_f32_32x32x16_bf16 v[2:17], v[162:165], v[142:145], v[2:17]
	v_exp_f32_e32 v112, v112
	v_exp_f32_e32 v113, v113
	s_nop 0
	v_mov_b32_e32 v130, v0
	s_nop 1
	v_permlane32_swap_b32_e32 v0, v130
	v_max_f32_e32 v0, v0, v130
	v_cmp_lt_f32_e32 vcc, s33, v0
	s_cmp_eq_u64 vcc, 0
	s_cselect_b64 s[12:13], -1, 0
	s_cbranch_vccnz .LBB0_248
	s_andn2_b64 vcc, exec, s[12:13]
	s_mov_b64 s[12:13], -1
	s_cbranch_vccz .LBB0_251

.LBB0_255:
	s_movk_i32 s87, 0x2000
	v_add_f32_e32 v147, v228, v0
	ds_read_b64_tr_b16 v[98:99], v226 offset:0
	ds_read_b64_tr_b16 v[100:101], v226 offset:512
	ds_read_b64_tr_b16 v[102:103], v226 offset:4096
	ds_read_b64_tr_b16 v[104:105], v226 offset:4608
	ds_read_b64_tr_b16 v[106:107], v226 offset:8192
	ds_read_b64_tr_b16 v[108:109], v226 offset:8704
	ds_read_b64_tr_b16 v[110:111], v226 offset:12288
	ds_read_b64_tr_b16 v[112:113], v226 offset:12800
	s_waitcnt lgkmcnt(6)
	s_nop 0
	v_max3_f32 v0, v130, s92, v131
	v_mfma_f32_32x32x16_bf16 v[50:65], v[174:177], v[98:101], v[50:65]
	v_exp_f32_e32 v130, v130
	v_exp_f32_e32 v131, v131
	ds_read_b64_tr_b16 v[98:99], v226 offset:1024
	ds_read_b64_tr_b16 v[100:101], v226 offset:1536
	s_waitcnt lgkmcnt(6)
	s_nop 0
	v_max3_f32 v0, v0, v132, v133
	v_mfma_f32_32x32x16_bf16 v[34:49], v[174:177], v[102:105], v[34:49]
	v_exp_f32_e32 v132, v132
	v_exp_f32_e32 v133, v133
	ds_read_b64_tr_b16 v[102:103], v226 offset:5120
	ds_read_b64_tr_b16 v[104:105], v226 offset:5632
	s_mov_b32 m0, s97
	s_waitcnt lgkmcnt(6)
	v_max3_f32 v0, v0, v134, v135
	buffer_load_dwordx4 v224, s[20:23], s58 offen lds
	v_mfma_f32_32x32x16_bf16 v[18:33], v[174:177], v[106:109], v[18:33]
	v_exp_f32_e32 v134, v134
	v_exp_f32_e32 v135, v135
	ds_read_b64_tr_b16 v[106:107], v226 offset:9216
	ds_read_b64_tr_b16 v[108:109], v226 offset:9728
	s_waitcnt lgkmcnt(6)
	s_nop 0
	v_max3_f32 v0, v0, v136, v137
	v_mfma_f32_32x32x16_bf16 v[2:17], v[174:177], v[110:113], v[2:17]
	v_exp_f32_e32 v136, v136
	v_exp_f32_e32 v137, v137
	ds_read_b64_tr_b16 v[110:111], v226 offset:13312
	ds_read_b64_tr_b16 v[112:113], v226 offset:13824
	s_waitcnt lgkmcnt(6)
	s_nop 0
	v_max3_f32 v0, v0, v138, v139
	v_mfma_f32_32x32x16_bf16 v[50:65], v[170:173], v[98:101], v[50:65]
	v_exp_f32_e32 v138, v138
	v_exp_f32_e32 v139, v139
	ds_read_b64_tr_b16 v[98:99], v226 offset:2048
	ds_read_b64_tr_b16 v[100:101], v226 offset:2560
	s_mov_b32 m0, s51
	v_readlane_b32 s10, v229, 25
	s_waitcnt lgkmcnt(6)
	v_max3_f32 v0, v0, v140, v141
	v_mfma_f32_32x32x16_bf16 v[34:49], v[170:173], v[102:105], v[34:49]
	v_exp_f32_e32 v140, v140
	s_nop 1
	buffer_load_dwordx4 v224, s[20:23], s10 offen lds
	v_exp_f32_e32 v141, v141
	ds_read_b64_tr_b16 v[102:103], v226 offset:6144
	ds_read_b64_tr_b16 v[104:105], v226 offset:6656
	s_waitcnt lgkmcnt(6)
	s_nop 0
	v_max3_f32 v0, v0, v142, v143
	v_mfma_f32_32x32x16_bf16 v[18:33], v[170:173], v[106:109], v[18:33]
	v_exp_f32_e32 v142, v142
	v_exp_f32_e32 v143, v143
	ds_read_b64_tr_b16 v[106:107], v226 offset:10240
	ds_read_b64_tr_b16 v[108:109], v226 offset:10752
	s_waitcnt lgkmcnt(6)
	s_nop 0
	v_max3_f32 v0, v0, v144, v145
	v_mfma_f32_32x32x16_bf16 v[2:17], v[170:173], v[110:113], v[2:17]
	v_exp_f32_e32 v144, v144
	v_exp_f32_e32 v145, v145
	ds_read_b64_tr_b16 v[110:111], v226 offset:14336
	ds_read_b64_tr_b16 v[112:113], v226 offset:14848
	s_mov_b32 m0, s31
	v_readlane_b32 s10, v229, 21
	s_waitcnt lgkmcnt(6)
	v_max3_f32 v0, v0, v82, v83
	v_mfma_f32_32x32x16_bf16 v[50:65], v[166:169], v[98:101], v[50:65]
	v_exp_f32_e32 v82, v82
	s_nop 1
	buffer_load_dwordx4 v223, s[20:23], s10 offen lds
	v_exp_f32_e32 v83, v83
	ds_read_b64_tr_b16 v[98:99], v226 offset:3072
	ds_read_b64_tr_b16 v[100:101], v226 offset:3584
	s_waitcnt lgkmcnt(6)
	s_nop 0
	v_max3_f32 v0, v0, v84, v85
	v_mfma_f32_32x32x16_bf16 v[34:49], v[166:169], v[102:105], v[34:49]
	v_exp_f32_e32 v84, v84
	v_exp_f32_e32 v85, v85
	ds_read_b64_tr_b16 v[102:103], v226 offset:7168
	ds_read_b64_tr_b16 v[104:105], v226 offset:7680
	s_waitcnt lgkmcnt(6)
	s_nop 0
	v_max3_f32 v0, v0, v86, v87
	v_mfma_f32_32x32x16_bf16 v[18:33], v[166:169], v[106:109], v[18:33]
	v_exp_f32_e32 v86, v86
	v_exp_f32_e32 v87, v87
	ds_read_b64_tr_b16 v[106:107], v226 offset:11264
	ds_read_b64_tr_b16 v[108:109], v226 offset:11776
	s_mov_b32 m0, s91
	v_readlane_b32 s10, v229, 24
	s_waitcnt lgkmcnt(6)
	v_max3_f32 v0, v0, v88, v89
	v_mfma_f32_32x32x16_bf16 v[2:17], v[166:169], v[110:113], v[2:17]
	v_exp_f32_e32 v88, v88
	s_nop 1
	buffer_load_dwordx4 v223, s[20:23], s10 offen lds
	v_exp_f32_e32 v89, v89
	ds_read_b64_tr_b16 v[110:111], v226 offset:15360
	ds_read_b64_tr_b16 v[112:113], v226 offset:15872
	s_waitcnt lgkmcnt(6)
	s_nop 0
	v_max3_f32 v0, v0, v90, v91
	v_mfma_f32_32x32x16_bf16 v[50:65], v[162:165], v[98:101], v[50:65]
	v_exp_f32_e32 v90, v90
	v_exp_f32_e32 v91, v91
	s_waitcnt lgkmcnt(4)
	s_nop 0
	v_max3_f32 v0, v0, v92, v93
	v_mfma_f32_32x32x16_bf16 v[34:49], v[162:165], v[102:105], v[34:49]
	v_exp_f32_e32 v92, v92
	v_exp_f32_e32 v93, v93
	s_waitcnt lgkmcnt(2)
	s_nop 0
	v_max3_f32 v0, v0, v94, v95
	v_mfma_f32_32x32x16_bf16 v[18:33], v[162:165], v[106:109], v[18:33]
	v_exp_f32_e32 v94, v94
	v_exp_f32_e32 v95, v95
	s_waitcnt lgkmcnt(0)
	s_nop 0
	v_max3_f32 v0, v0, v96, v97
	v_mfma_f32_32x32x16_bf16 v[2:17], v[162:165], v[110:113], v[2:17]
	v_exp_f32_e32 v96, v96
	v_exp_f32_e32 v97, v97
	s_nop 0
	v_mov_b32_e32 v98, v0
	s_nop 1
	v_permlane32_swap_b32_e32 v0, v98
	v_max_f32_e32 v0, v0, v98
	v_cmp_lt_f32_e32 vcc, s33, v0
	s_cmp_lg_u64 vcc, 0
	s_cselect_b64 s[12:13], -1, 0
	s_cbranch_vccz .LBB0_260
	v_max_f32_e32 v0, v0, v0
	v_max_f32_e32 v98, 0, v0
	v_exp_f32_e64 v0, -v98
	s_and_saveexec_b64 s[80:81], s[4:5]
	s_movk_i32 s31, 0x1000
	ds_write_b32 v213, v0
	s_or_b64 exec, exec, s[80:81]
	s_waitcnt lgkmcnt(0)
	v_add_f32_e32 v222, v222, v98
	ds_read_b128 v[98:101], v212
	ds_read_b128 v[102:105], v212 offset:32
	ds_read_b128 v[106:109], v212 offset:64
	ds_read_b128 v[110:113], v212 offset:96
	v_mul_f32_e32 v147, v147, v0
	s_waitcnt lgkmcnt(3)
	v_pk_mul_f32 v[52:53], v[52:53], v[100:101]
	s_waitcnt lgkmcnt(2)
	v_pk_mul_f32 v[56:57], v[56:57], v[104:105]
	s_waitcnt lgkmcnt(1)
	v_pk_mul_f32 v[60:61], v[60:61], v[108:109]
	s_waitcnt lgkmcnt(0)
	v_pk_mul_f32 v[64:65], v[64:65], v[112:113]
	v_pk_mul_f32 v[62:63], v[62:63], v[110:111]
	v_pk_mul_f32 v[58:59], v[58:59], v[106:107]
	v_pk_mul_f32 v[54:55], v[54:55], v[102:103]
	v_pk_mul_f32 v[50:51], v[50:51], v[98:99]
	v_pk_mul_f32 v[48:49], v[48:49], v[112:113]
	v_pk_mul_f32 v[44:45], v[44:45], v[108:109]
	v_pk_mul_f32 v[40:41], v[40:41], v[104:105]
	v_pk_mul_f32 v[36:37], v[36:37], v[100:101]
	v_pk_mul_f32 v[46:47], v[46:47], v[110:111]
	v_pk_mul_f32 v[42:43], v[42:43], v[106:107]
	v_pk_mul_f32 v[38:39], v[38:39], v[102:103]
	v_pk_mul_f32 v[34:35], v[34:35], v[98:99]
	v_pk_mul_f32 v[32:33], v[32:33], v[112:113]
	v_pk_mul_f32 v[28:29], v[28:29], v[108:109]
	v_pk_mul_f32 v[24:25], v[24:25], v[104:105]
	v_pk_mul_f32 v[20:21], v[20:21], v[100:101]
	v_pk_mul_f32 v[30:31], v[30:31], v[110:111]
	v_pk_mul_f32 v[26:27], v[26:27], v[106:107]
	v_pk_mul_f32 v[22:23], v[22:23], v[102:103]
	v_pk_mul_f32 v[18:19], v[18:19], v[98:99]
	v_pk_mul_f32 v[16:17], v[16:17], v[112:113]
	v_pk_mul_f32 v[12:13], v[12:13], v[108:109]
	v_pk_mul_f32 v[8:9], v[8:9], v[104:105]
	v_pk_mul_f32 v[4:5], v[4:5], v[100:101]
	v_pk_mul_f32 v[14:15], v[14:15], v[110:111]
	v_pk_mul_f32 v[10:11], v[10:11], v[106:107]
	v_pk_mul_f32 v[6:7], v[6:7], v[102:103]
	v_pk_mul_f32 v[2:3], v[2:3], v[98:99]
	v_pk_mul_f32 v[144:145], v[144:145], v[0:1] op_sel_hi:[1,0]
	v_pk_mul_f32 v[142:143], v[142:143], v[0:1] op_sel_hi:[1,0]
	v_pk_mul_f32 v[140:141], v[140:141], v[0:1] op_sel_hi:[1,0]
	v_pk_mul_f32 v[138:139], v[138:139], v[0:1] op_sel_hi:[1,0]
	v_pk_mul_f32 v[136:137], v[136:137], v[0:1] op_sel_hi:[1,0]
	v_pk_mul_f32 v[134:135], v[134:135], v[0:1] op_sel_hi:[1,0]
	v_pk_mul_f32 v[132:133], v[132:133], v[0:1] op_sel_hi:[1,0]
	v_pk_mul_f32 v[130:131], v[130:131], v[0:1] op_sel_hi:[1,0]
	v_pk_mul_f32 v[96:97], v[96:97], v[0:1] op_sel_hi:[1,0]
	v_pk_mul_f32 v[94:95], v[94:95], v[0:1] op_sel_hi:[1,0]
	v_pk_mul_f32 v[92:93], v[92:93], v[0:1] op_sel_hi:[1,0]
	v_pk_mul_f32 v[90:91], v[90:91], v[0:1] op_sel_hi:[1,0]
	v_pk_mul_f32 v[88:89], v[88:89], v[0:1] op_sel_hi:[1,0]
	v_pk_mul_f32 v[86:87], v[86:87], v[0:1] op_sel_hi:[1,0]
	v_pk_mul_f32 v[84:85], v[84:85], v[0:1] op_sel_hi:[1,0]
	v_pk_mul_f32 v[82:83], v[82:83], v[0:1] op_sel_hi:[1,0]
	s_andn2_b64 vcc, exec, s[12:13]
	s_cbranch_vccnz .LBB0_261

.LBB0_268:
	v_add_f32_e32 v130, v147, v0
	ds_read_b64_tr_b16 v[82:83], v225 offset:0
	ds_read_b64_tr_b16 v[84:85], v225 offset:512
	ds_read_b64_tr_b16 v[86:87], v225 offset:4096
	ds_read_b64_tr_b16 v[88:89], v225 offset:4608
	ds_read_b64_tr_b16 v[90:91], v225 offset:8192
	ds_read_b64_tr_b16 v[92:93], v225 offset:8704
	ds_read_b64_tr_b16 v[94:95], v225 offset:12288
	ds_read_b64_tr_b16 v[96:97], v225 offset:12800
	s_waitcnt lgkmcnt(6)
	s_nop 0
	v_max3_f32 v0, v114, s92, v115
	v_mfma_f32_32x32x16_bf16 v[50:65], v[174:177], v[82:85], v[50:65]
	v_exp_f32_e32 v114, v114
	v_exp_f32_e32 v115, v115
	ds_read_b64_tr_b16 v[82:83], v225 offset:1024
	ds_read_b64_tr_b16 v[84:85], v225 offset:1536
	s_waitcnt lgkmcnt(6)
	s_nop 0
	v_max3_f32 v0, v0, v116, v117
	v_mfma_f32_32x32x16_bf16 v[34:49], v[174:177], v[86:89], v[34:49]
	v_exp_f32_e32 v116, v116
	v_exp_f32_e32 v117, v117
	ds_read_b64_tr_b16 v[86:87], v225 offset:5120
	ds_read_b64_tr_b16 v[88:89], v225 offset:5632
	s_waitcnt lgkmcnt(6)
	s_nop 0
	v_max3_f32 v0, v0, v118, v119
	v_mfma_f32_32x32x16_bf16 v[18:33], v[174:177], v[90:93], v[18:33]
	v_exp_f32_e32 v118, v118
	v_exp_f32_e32 v119, v119
	ds_read_b64_tr_b16 v[90:91], v225 offset:9216
	ds_read_b64_tr_b16 v[92:93], v225 offset:9728
	s_waitcnt lgkmcnt(6)
	s_nop 0
	v_max3_f32 v0, v0, v120, v121
	v_mfma_f32_32x32x16_bf16 v[2:17], v[174:177], v[94:97], v[2:17]
	v_exp_f32_e32 v120, v120
	v_exp_f32_e32 v121, v121
	ds_read_b64_tr_b16 v[94:95], v225 offset:13312
	ds_read_b64_tr_b16 v[96:97], v225 offset:13824
	s_waitcnt lgkmcnt(6)
	s_nop 0
	v_max3_f32 v0, v0, v122, v123
	v_mfma_f32_32x32x16_bf16 v[50:65], v[170:173], v[82:85], v[50:65]
	v_exp_f32_e32 v122, v122
	v_exp_f32_e32 v123, v123
	ds_read_b64_tr_b16 v[82:83], v225 offset:2048
	ds_read_b64_tr_b16 v[84:85], v225 offset:2560
	s_waitcnt lgkmcnt(6)
	s_nop 0
	v_max3_f32 v0, v0, v124, v125
	v_mfma_f32_32x32x16_bf16 v[34:49], v[170:173], v[86:89], v[34:49]
	v_exp_f32_e32 v124, v124
	v_exp_f32_e32 v125, v125
	ds_read_b64_tr_b16 v[86:87], v225 offset:6144
	ds_read_b64_tr_b16 v[88:89], v225 offset:6656
	s_waitcnt lgkmcnt(6)
	s_nop 0
	v_max3_f32 v0, v0, v126, v127
	v_mfma_f32_32x32x16_bf16 v[18:33], v[170:173], v[90:93], v[18:33]
	v_exp_f32_e32 v126, v126
	v_exp_f32_e32 v127, v127
	ds_read_b64_tr_b16 v[90:91], v225 offset:10240
	ds_read_b64_tr_b16 v[92:93], v225 offset:10752
	s_waitcnt lgkmcnt(6)
	s_nop 0
	v_max3_f32 v0, v0, v128, v129
	v_mfma_f32_32x32x16_bf16 v[2:17], v[170:173], v[94:97], v[2:17]
	v_exp_f32_e32 v128, v128
	v_exp_f32_e32 v129, v129
	ds_read_b64_tr_b16 v[94:95], v225 offset:14336
	ds_read_b64_tr_b16 v[96:97], v225 offset:14848
	s_waitcnt lgkmcnt(6)
	s_nop 0
	v_max3_f32 v0, v0, v98, v99
	v_mfma_f32_32x32x16_bf16 v[50:65], v[166:169], v[82:85], v[50:65]
	v_exp_f32_e32 v98, v98
	v_exp_f32_e32 v99, v99
	ds_read_b64_tr_b16 v[82:83], v225 offset:3072
	ds_read_b64_tr_b16 v[84:85], v225 offset:3584
	s_waitcnt lgkmcnt(6)
	s_nop 0
	v_max3_f32 v0, v0, v100, v101
	v_mfma_f32_32x32x16_bf16 v[34:49], v[166:169], v[86:89], v[34:49]
	v_exp_f32_e32 v100, v100
	v_exp_f32_e32 v101, v101
	ds_read_b64_tr_b16 v[86:87], v225 offset:7168
	ds_read_b64_tr_b16 v[88:89], v225 offset:7680
	s_waitcnt lgkmcnt(6)
	s_nop 0
	v_max3_f32 v0, v0, v102, v103
	v_mfma_f32_32x32x16_bf16 v[18:33], v[166:169], v[90:93], v[18:33]
	v_exp_f32_e32 v102, v102
	v_exp_f32_e32 v103, v103
	ds_read_b64_tr_b16 v[90:91], v225 offset:11264
	ds_read_b64_tr_b16 v[92:93], v225 offset:11776
	s_waitcnt lgkmcnt(6)
	s_nop 0
	v_max3_f32 v0, v0, v104, v105
	v_mfma_f32_32x32x16_bf16 v[2:17], v[166:169], v[94:97], v[2:17]
	v_exp_f32_e32 v104, v104
	v_exp_f32_e32 v105, v105
	ds_read_b64_tr_b16 v[94:95], v225 offset:15360
	ds_read_b64_tr_b16 v[96:97], v225 offset:15872
	s_waitcnt lgkmcnt(6)
	s_nop 0
	v_max3_f32 v0, v0, v106, v107
	v_mfma_f32_32x32x16_bf16 v[50:65], v[162:165], v[82:85], v[50:65]
	v_exp_f32_e32 v106, v106
	v_exp_f32_e32 v107, v107
	s_waitcnt lgkmcnt(4)
	s_nop 0
	v_max3_f32 v0, v0, v108, v109
	v_mfma_f32_32x32x16_bf16 v[34:49], v[162:165], v[86:89], v[34:49]
	v_exp_f32_e32 v108, v108
	v_exp_f32_e32 v109, v109
	s_waitcnt lgkmcnt(2)
	s_nop 0
	v_max3_f32 v0, v0, v110, v111
	v_mfma_f32_32x32x16_bf16 v[18:33], v[162:165], v[90:93], v[18:33]
	v_exp_f32_e32 v110, v110
	v_exp_f32_e32 v111, v111
	s_waitcnt lgkmcnt(0)
	s_nop 0
	v_max3_f32 v0, v0, v112, v113
	v_mfma_f32_32x32x16_bf16 v[2:17], v[162:165], v[94:97], v[2:17]
	v_exp_f32_e32 v112, v112
	v_exp_f32_e32 v113, v113
	s_nop 0
	v_mov_b32_e32 v82, v0
	s_nop 1
	v_permlane32_swap_b32_e32 v0, v82
	v_max_f32_e32 v0, v0, v82
	v_cmp_lt_f32_e32 vcc, s33, v0
	s_cmp_lg_u64 vcc, 0
	s_cselect_b64 s[12:13], -1, 0
	s_cbranch_vccz .LBB0_272
	v_max_f32_e32 v0, v0, v0
	v_max_f32_e32 v82, 0, v0
	v_exp_f32_e64 v0, -v82
	s_and_saveexec_b64 s[20:21], s[4:5]
	ds_write_b32 v213, v0
	s_or_b64 exec, exec, s[20:21]
	s_waitcnt lgkmcnt(0)
	v_add_f32_e32 v222, v222, v82
	ds_read_b128 v[82:85], v212
	ds_read_b128 v[86:89], v212 offset:32
	ds_read_b128 v[90:93], v212 offset:64
	ds_read_b128 v[94:97], v212 offset:96
	v_mul_f32_e32 v130, v130, v0
	s_waitcnt lgkmcnt(3)
	v_pk_mul_f32 v[52:53], v[52:53], v[84:85]
	s_waitcnt lgkmcnt(2)
	v_pk_mul_f32 v[56:57], v[56:57], v[88:89]
	s_waitcnt lgkmcnt(1)
	v_pk_mul_f32 v[60:61], v[60:61], v[92:93]
	s_waitcnt lgkmcnt(0)
	v_pk_mul_f32 v[64:65], v[64:65], v[96:97]
	v_pk_mul_f32 v[62:63], v[62:63], v[94:95]
	v_pk_mul_f32 v[58:59], v[58:59], v[90:91]
	v_pk_mul_f32 v[54:55], v[54:55], v[86:87]
	v_pk_mul_f32 v[50:51], v[50:51], v[82:83]
	v_pk_mul_f32 v[48:49], v[48:49], v[96:97]
	v_pk_mul_f32 v[44:45], v[44:45], v[92:93]
	v_pk_mul_f32 v[40:41], v[40:41], v[88:89]
	v_pk_mul_f32 v[36:37], v[36:37], v[84:85]
	v_pk_mul_f32 v[46:47], v[46:47], v[94:95]
	v_pk_mul_f32 v[42:43], v[42:43], v[90:91]
	v_pk_mul_f32 v[38:39], v[38:39], v[86:87]
	v_pk_mul_f32 v[34:35], v[34:35], v[82:83]
	v_pk_mul_f32 v[32:33], v[32:33], v[96:97]
	v_pk_mul_f32 v[28:29], v[28:29], v[92:93]
	v_pk_mul_f32 v[24:25], v[24:25], v[88:89]
	v_pk_mul_f32 v[20:21], v[20:21], v[84:85]
	v_pk_mul_f32 v[30:31], v[30:31], v[94:95]
	v_pk_mul_f32 v[26:27], v[26:27], v[90:91]
	v_pk_mul_f32 v[22:23], v[22:23], v[86:87]
	v_pk_mul_f32 v[18:19], v[18:19], v[82:83]
	v_pk_mul_f32 v[16:17], v[16:17], v[96:97]
	v_pk_mul_f32 v[12:13], v[12:13], v[92:93]
	v_pk_mul_f32 v[8:9], v[8:9], v[88:89]
	v_pk_mul_f32 v[4:5], v[4:5], v[84:85]
	v_pk_mul_f32 v[14:15], v[14:15], v[94:95]
	v_pk_mul_f32 v[10:11], v[10:11], v[90:91]
	v_pk_mul_f32 v[6:7], v[6:7], v[86:87]
	v_pk_mul_f32 v[2:3], v[2:3], v[82:83]
	v_pk_mul_f32 v[128:129], v[128:129], v[0:1] op_sel_hi:[1,0]
	v_pk_mul_f32 v[126:127], v[126:127], v[0:1] op_sel_hi:[1,0]
	v_pk_mul_f32 v[124:125], v[124:125], v[0:1] op_sel_hi:[1,0]
	v_pk_mul_f32 v[122:123], v[122:123], v[0:1] op_sel_hi:[1,0]
	v_pk_mul_f32 v[120:121], v[120:121], v[0:1] op_sel_hi:[1,0]
	v_pk_mul_f32 v[118:119], v[118:119], v[0:1] op_sel_hi:[1,0]
	v_pk_mul_f32 v[116:117], v[116:117], v[0:1] op_sel_hi:[1,0]
	v_pk_mul_f32 v[114:115], v[114:115], v[0:1] op_sel_hi:[1,0]
	v_pk_mul_f32 v[112:113], v[112:113], v[0:1] op_sel_hi:[1,0]
	v_pk_mul_f32 v[110:111], v[110:111], v[0:1] op_sel_hi:[1,0]
	v_pk_mul_f32 v[108:109], v[108:109], v[0:1] op_sel_hi:[1,0]
	v_pk_mul_f32 v[106:107], v[106:107], v[0:1] op_sel_hi:[1,0]
	v_pk_mul_f32 v[104:105], v[104:105], v[0:1] op_sel_hi:[1,0]
	v_pk_mul_f32 v[102:103], v[102:103], v[0:1] op_sel_hi:[1,0]
	v_pk_mul_f32 v[100:101], v[100:101], v[0:1] op_sel_hi:[1,0]
	v_pk_mul_f32 v[98:99], v[98:99], v[0:1] op_sel_hi:[1,0]

.LBB0_279:
	v_add_f32_e32 v98, v130, v0
	ds_read_b64_tr_b16 v[100:101], v215 offset:0
	ds_read_b64_tr_b16 v[102:103], v215 offset:512
	ds_read_b64_tr_b16 v[104:105], v215 offset:4096
	ds_read_b64_tr_b16 v[106:107], v215 offset:4608
	ds_read_b64_tr_b16 v[108:109], v215 offset:8192
	ds_read_b64_tr_b16 v[110:111], v215 offset:8704
	ds_read_b64_tr_b16 v[112:113], v215 offset:12288
	ds_read_b64_tr_b16 v[114:115], v215 offset:12800
	s_waitcnt lgkmcnt(6)
	s_nop 0
	v_max3_f32 v0, v82, s92, v83
	v_mfma_f32_32x32x16_bf16 v[50:65], v[174:177], v[100:103], v[50:65]
	v_exp_f32_e32 v82, v82
	v_exp_f32_e32 v83, v83
	ds_read_b64_tr_b16 v[100:101], v215 offset:1024
	ds_read_b64_tr_b16 v[102:103], v215 offset:1536
	s_waitcnt lgkmcnt(6)
	s_nop 0
	v_max3_f32 v0, v0, v84, v85
	v_mfma_f32_32x32x16_bf16 v[34:49], v[174:177], v[104:107], v[34:49]
	v_exp_f32_e32 v84, v84
	v_exp_f32_e32 v85, v85
	ds_read_b64_tr_b16 v[104:105], v215 offset:5120
	ds_read_b64_tr_b16 v[106:107], v215 offset:5632
	s_waitcnt lgkmcnt(6)
	s_nop 0
	v_max3_f32 v0, v0, v86, v87
	v_mfma_f32_32x32x16_bf16 v[18:33], v[174:177], v[108:111], v[18:33]
	v_exp_f32_e32 v86, v86
	v_exp_f32_e32 v87, v87
	ds_read_b64_tr_b16 v[108:109], v215 offset:9216
	ds_read_b64_tr_b16 v[110:111], v215 offset:9728
	s_waitcnt lgkmcnt(6)
	s_nop 0
	v_max3_f32 v0, v0, v88, v89
	v_mfma_f32_32x32x16_bf16 v[2:17], v[174:177], v[112:115], v[2:17]
	v_exp_f32_e32 v88, v88
	v_exp_f32_e32 v89, v89
	ds_read_b64_tr_b16 v[112:113], v215 offset:13312
	ds_read_b64_tr_b16 v[114:115], v215 offset:13824
	s_waitcnt lgkmcnt(6)
	s_nop 0
	v_max3_f32 v0, v0, v90, v91
	v_mfma_f32_32x32x16_bf16 v[50:65], v[170:173], v[100:103], v[50:65]
	v_exp_f32_e32 v90, v90
	v_exp_f32_e32 v91, v91
	ds_read_b64_tr_b16 v[100:101], v215 offset:2048
	ds_read_b64_tr_b16 v[102:103], v215 offset:2560
	s_waitcnt lgkmcnt(6)
	s_nop 0
	v_max3_f32 v0, v0, v92, v93
	v_mfma_f32_32x32x16_bf16 v[34:49], v[170:173], v[104:107], v[34:49]
	v_exp_f32_e32 v92, v92
	v_exp_f32_e32 v93, v93
	ds_read_b64_tr_b16 v[104:105], v215 offset:6144
	ds_read_b64_tr_b16 v[106:107], v215 offset:6656
	s_waitcnt lgkmcnt(6)
	s_nop 0
	v_max3_f32 v0, v0, v94, v95
	v_mfma_f32_32x32x16_bf16 v[18:33], v[170:173], v[108:111], v[18:33]
	v_exp_f32_e32 v94, v94
	v_exp_f32_e32 v95, v95
	ds_read_b64_tr_b16 v[108:109], v215 offset:10240
	ds_read_b64_tr_b16 v[110:111], v215 offset:10752
	s_waitcnt lgkmcnt(6)
	s_nop 0
	v_max3_f32 v0, v0, v96, v97
	v_mfma_f32_32x32x16_bf16 v[2:17], v[170:173], v[112:115], v[2:17]
	v_exp_f32_e32 v96, v96
	v_exp_f32_e32 v97, v97
	ds_read_b64_tr_b16 v[112:113], v215 offset:14336
	ds_read_b64_tr_b16 v[114:115], v215 offset:14848
	s_waitcnt lgkmcnt(6)
	s_nop 0
	v_max3_f32 v0, v0, v66, v67
	v_mfma_f32_32x32x16_bf16 v[50:65], v[166:169], v[100:103], v[50:65]
	v_exp_f32_e32 v66, v66
	v_exp_f32_e32 v67, v67
	ds_read_b64_tr_b16 v[100:101], v215 offset:3072
	ds_read_b64_tr_b16 v[102:103], v215 offset:3584
	s_waitcnt lgkmcnt(6)
	s_nop 0
	v_max3_f32 v0, v0, v68, v69
	v_mfma_f32_32x32x16_bf16 v[34:49], v[166:169], v[104:107], v[34:49]
	v_exp_f32_e32 v68, v68
	v_exp_f32_e32 v69, v69
	ds_read_b64_tr_b16 v[104:105], v215 offset:7168
	ds_read_b64_tr_b16 v[106:107], v215 offset:7680
	s_waitcnt lgkmcnt(6)
	s_nop 0
	v_max3_f32 v0, v0, v70, v71
	v_mfma_f32_32x32x16_bf16 v[18:33], v[166:169], v[108:111], v[18:33]
	v_exp_f32_e32 v70, v70
	v_exp_f32_e32 v71, v71
	ds_read_b64_tr_b16 v[108:109], v215 offset:11264
	ds_read_b64_tr_b16 v[110:111], v215 offset:11776
	s_waitcnt lgkmcnt(6)
	s_nop 0
	v_max3_f32 v0, v0, v72, v73
	v_mfma_f32_32x32x16_bf16 v[2:17], v[166:169], v[112:115], v[2:17]
	v_exp_f32_e32 v72, v72
	v_exp_f32_e32 v73, v73
	ds_read_b64_tr_b16 v[112:113], v215 offset:15360
	ds_read_b64_tr_b16 v[114:115], v215 offset:15872
	s_waitcnt lgkmcnt(6)
	s_nop 0
	v_max3_f32 v0, v0, v74, v75
	v_mfma_f32_32x32x16_bf16 v[50:65], v[162:165], v[100:103], v[50:65]
	v_exp_f32_e32 v74, v74
	v_exp_f32_e32 v75, v75
	s_waitcnt lgkmcnt(4)
	s_nop 0
	v_max3_f32 v0, v0, v76, v77
	v_mfma_f32_32x32x16_bf16 v[34:49], v[162:165], v[104:107], v[34:49]
	v_exp_f32_e32 v76, v76
	v_exp_f32_e32 v77, v77
	s_waitcnt lgkmcnt(2)
	s_nop 0
	v_max3_f32 v0, v0, v78, v79
	v_mfma_f32_32x32x16_bf16 v[18:33], v[162:165], v[108:111], v[18:33]
	v_exp_f32_e32 v78, v78
	v_exp_f32_e32 v79, v79
	s_waitcnt lgkmcnt(0)
	s_nop 0
	v_max3_f32 v0, v0, v80, v81
	v_mfma_f32_32x32x16_bf16 v[2:17], v[162:165], v[112:115], v[2:17]
	v_exp_f32_e32 v80, v80
	v_exp_f32_e32 v81, v81
	s_nop 0
	v_mov_b32_e32 v99, v0
	s_nop 1
	v_permlane32_swap_b32_e32 v0, v99
	v_max_f32_e32 v0, v0, v99
	v_cmp_lt_f32_e32 vcc, s33, v0
	s_cbranch_vccz .LBB0_283
	v_max_f32_e32 v0, v0, v0
	v_max_f32_e32 v0, 0, v0
	v_exp_f32_e64 v0, -v0
	s_and_saveexec_b64 s[6:7], s[4:5]
	ds_write_b32 v213, v0
	s_or_b64 exec, exec, s[6:7]
	s_waitcnt lgkmcnt(0)
	ds_read_b128 v[100:103], v212 offset:96
	ds_read_b128 v[104:107], v212 offset:64
	ds_read_b128 v[108:111], v212 offset:32
	ds_read_b128 v[112:115], v212
	v_mul_f32_e32 v98, v98, v0
	s_waitcnt lgkmcnt(3)
	v_pk_mul_f32 v[64:65], v[64:65], v[102:103]
	s_waitcnt lgkmcnt(2)
	v_pk_mul_f32 v[60:61], v[60:61], v[106:107]
	s_waitcnt lgkmcnt(1)
	v_pk_mul_f32 v[56:57], v[56:57], v[110:111]
	s_waitcnt lgkmcnt(0)
	v_pk_mul_f32 v[52:53], v[52:53], v[114:115]
	v_pk_mul_f32 v[62:63], v[62:63], v[100:101]
	v_pk_mul_f32 v[58:59], v[58:59], v[104:105]
	v_pk_mul_f32 v[54:55], v[54:55], v[108:109]
	v_pk_mul_f32 v[50:51], v[50:51], v[112:113]
	v_pk_mul_f32 v[48:49], v[48:49], v[102:103]
	v_pk_mul_f32 v[44:45], v[44:45], v[106:107]
	v_pk_mul_f32 v[40:41], v[40:41], v[110:111]
	v_pk_mul_f32 v[36:37], v[36:37], v[114:115]
	v_pk_mul_f32 v[46:47], v[46:47], v[100:101]
	v_pk_mul_f32 v[42:43], v[42:43], v[104:105]
	v_pk_mul_f32 v[38:39], v[38:39], v[108:109]
	v_pk_mul_f32 v[34:35], v[34:35], v[112:113]
	v_pk_mul_f32 v[32:33], v[32:33], v[102:103]
	v_pk_mul_f32 v[28:29], v[28:29], v[106:107]
	v_pk_mul_f32 v[24:25], v[24:25], v[110:111]
	v_pk_mul_f32 v[20:21], v[20:21], v[114:115]
	v_pk_mul_f32 v[30:31], v[30:31], v[100:101]
	v_pk_mul_f32 v[26:27], v[26:27], v[104:105]
	v_pk_mul_f32 v[22:23], v[22:23], v[108:109]
	v_pk_mul_f32 v[18:19], v[18:19], v[112:113]
	v_pk_mul_f32 v[16:17], v[16:17], v[102:103]
	v_pk_mul_f32 v[12:13], v[12:13], v[106:107]
	v_pk_mul_f32 v[8:9], v[8:9], v[110:111]
	v_pk_mul_f32 v[4:5], v[4:5], v[114:115]
	v_pk_mul_f32 v[14:15], v[14:15], v[100:101]
	v_pk_mul_f32 v[10:11], v[10:11], v[104:105]
	v_pk_mul_f32 v[6:7], v[6:7], v[108:109]
	v_pk_mul_f32 v[2:3], v[2:3], v[112:113]
	v_pk_mul_f32 v[96:97], v[96:97], v[0:1] op_sel_hi:[1,0]
	v_pk_mul_f32 v[94:95], v[94:95], v[0:1] op_sel_hi:[1,0]
	v_pk_mul_f32 v[92:93], v[92:93], v[0:1] op_sel_hi:[1,0]
	v_pk_mul_f32 v[90:91], v[90:91], v[0:1] op_sel_hi:[1,0]
	v_pk_mul_f32 v[88:89], v[88:89], v[0:1] op_sel_hi:[1,0]
	v_pk_mul_f32 v[86:87], v[86:87], v[0:1] op_sel_hi:[1,0]
	v_pk_mul_f32 v[84:85], v[84:85], v[0:1] op_sel_hi:[1,0]
	v_pk_mul_f32 v[82:83], v[82:83], v[0:1] op_sel_hi:[1,0]
	v_pk_mul_f32 v[80:81], v[80:81], v[0:1] op_sel_hi:[1,0]
	v_pk_mul_f32 v[78:79], v[78:79], v[0:1] op_sel_hi:[1,0]
	v_pk_mul_f32 v[76:77], v[76:77], v[0:1] op_sel_hi:[1,0]
	v_pk_mul_f32 v[74:75], v[74:75], v[0:1] op_sel_hi:[1,0]
	v_pk_mul_f32 v[72:73], v[72:73], v[0:1] op_sel_hi:[1,0]
	v_pk_mul_f32 v[70:71], v[70:71], v[0:1] op_sel_hi:[1,0]
	v_pk_mul_f32 v[68:69], v[68:69], v[0:1] op_sel_hi:[1,0]
	v_pk_mul_f32 v[66:67], v[66:67], v[0:1] op_sel_hi:[1,0]
